# add QK K-fragment prefetch (depth 3 in light-block loop, depth 2 with LDS-spilled registers in heavy-block loop)
# baseline (speedup 1.0000x reference)
; #define LAS __attribute__((address_space(3)))
; #define SBAR() __builtin_amdgcn_sched_barrier(0)
; __device__ __forceinline__ int v_rd_base(int lane) { return ((lane & 3) << 3) | (((lane >> 2) & 3) << 6) | (((lane >> 4) & 1) << 5) | (((lane >> 5) & 1) << 8); }
; #define WAITV_BAR(N) asm volatile("s_waitcnt vmcnt(" #N ") lgkmcnt(0)\n\ts_barrier" ::: "memory")
; #define DMA_K(t, slot) do { _Pragma("unroll") for (int i_ = 0; i_ < 2; ++i_) __builtin_amdgcn_global_load_lds((const unsigned*)((const char*)Kh + (size_t)(t) * (KVBLK * D * 2) + dof.k[i_]), \
;         (LAS unsigned*)((LAS unsigned char*)lds3 + OFF_K + (slot) + (wid * 2 + i_) * 1024), 16, 0, 0); } while (0)
; __device__ __forceinline__ void fox_prime(const BlockRef& cur, char* lds, Seam& S, const int tid) {
;     const int wid = __builtin_amdgcn_readfirstlane(tid >> 6), lane = tid & 63, r32 = lane & 31, hi = lane >> 5;
;     LAS unsigned char* lds3 = (LAS unsigned char*)lds; const DmaOff dof = dma_offsets(wid, lane);
;     const bf16_t* Kh = cur.K; const bf16_t* Vh = cur.V;
; #pragma unroll
;     for (int d0 = 0; d0 < 8; ++d0) S.qr[d0] = load8(cur.Q + (size_t)(wid * QBLK + r32) * LD + d0 * 16 + hi * 8);
;     SBAR(); DMA_K(0, 0); DMA_K(1, SLOT); DMA_V(0, 0); SBAR();
;     WAITV_BAR(0);
; }
; __device__ __forceinline__ void fox_block(const BlockRef& cur, const BlockRef& nxt, char* lds, Seam& S, const int tid) {
;     const int wid = __builtin_amdgcn_readfirstlane(tid >> 6), lane = tid & 63, r32 = lane & 31, hi = lane >> 5;
;     const int NT = cur.P0 / KVBLK + 4;
;     const int qlo = cur.P0 + wid * QBLK, qm = qlo + r32 - 4 * hi;
;     char* V_lds = lds; char* K_lds = lds + OFF_K; LAS unsigned char* lds3 = (LAS unsigned char*)lds;
;     float* ws = (float*)(lds + OFF_WS) + wid * 64; float* li_l = ws, * al_l = ws + 32;
;     const LAS float* ctab = (const LAS float*)(LAS char*)(lds + OFF_C);
;     float m_reg = -1e30f, l_reg = 0; f32x16 o[4] = {};
;     const DmaOff dof = dma_offsets(wid, lane);
;     const int vb0 = (int)(uintptr_t)V_lds + v_rd_base(lane);
;     const bf16_t* Kh = cur.K; const bf16_t* Vh = cur.V;
;     ...
;     f32x16 pA0, pA1, pB0, pB1; float mnA, mnB, alA, alB; bf16x8 pa0, pa1, pa2, pa3;
;     int s_prev = 0, s_cur = 0, s_next = SLOT, s_nn = 2 * SLOT;
;     SBAR(); DMA_K(2, s_nn); DMA_V(1, s_next); SBAR();
;     qkt(pA0, pA1, K_lds + s_cur, r32, hi, S.qr, CTP(0));
.LBB0_520:
	s_or_b64 exec, exec, s[2:3]
	s_lshl_b32 s2, s60, 8
	v_writelane_b32 v247, s60, 11
	s_and_b32 s2, s2, 0x700
	s_and_b32 s3, s4, 15
	s_lshl_b32 s5, s11, 12
	v_writelane_b32 v247, s2, 12
	s_xor_b32 s4, s2, 0xf00
	v_writelane_b32 v247, s5, 13
	s_or_b32 s6, s4, s5
	v_readlane_b32 s12, v248, 63
	s_ashr_i32 s7, s6, 31
	v_readlane_b32 s13, v247, 0
	s_lshl_b64 s[6:7], s[6:7], 11
	s_mov_b32 s11, s13
	s_lshl_b32 s10, s10, 7
	v_writelane_b32 v248, s10, 63
	s_or_b32 s6, s6, s10
	s_lshl_b64 s[78:79], s[6:7], 1
	s_add_u32 s6, s93, s78
	v_readlane_b32 s2, v248, 37
	s_addc_u32 s7, s2, s79
	s_mul_hi_i32 s2, s9, 0x104000
	s_mul_i32 s9, s9, 0x104000
	v_readlane_b32 s5, v248, 38
	s_add_u32 s30, s5, s9
	v_readlane_b32 s5, v248, 39
	s_addc_u32 s31, s5, s2
	v_readlane_b32 s5, v248, 40
	v_writelane_b32 v247, s11, 0
	s_add_u32 s10, s5, s9
	v_readlane_b32 s5, v248, 41
	s_addc_u32 s11, s5, s2
	v_readfirstlane_b32 s2, v155
	s_ashr_i32 s9, s2, 6
	v_and_b32_e32 v199, 31, v155
	s_lshl_b32 s14, s9, 5
	v_or_b32_e32 v0, s14, v199
	v_ashrrev_i32_e32 v1, 31, v0
	v_lshlrev_b64 v[132:133], 12, v[0:1]
	v_lshrrev_b32_e32 v2, 1, v155
	v_lshl_add_u64 v[0:1], s[6:7], 0, v[132:133]
	v_and_b32_e32 v128, 16, v2
	v_lshl_add_u64 v[0:1], v[0:1], 0, v[128:129]
	s_waitcnt lgkmcnt(0)
	s_barrier
	global_load_dwordx4 v[96:99], v[0:1], off
	global_load_dwordx4 v[100:103], v[0:1], off offset:32
	global_load_dwordx4 v[104:107], v[0:1], off offset:64
	global_load_dwordx4 v[108:111], v[0:1], off offset:96
	global_load_dwordx4 v[112:115], v[0:1], off offset:128
	global_load_dwordx4 v[116:119], v[0:1], off offset:160
	global_load_dwordx4 v[120:123], v[0:1], off offset:192
	global_load_dwordx4 v[124:127], v[0:1], off offset:224
	s_lshl_b32 s5, s9, 7
	v_or_b32_e32 v1, s5, v198
	s_ashr_i32 s5, s5, 4
	v_lshrrev_b32_e32 v191, 2, v198
	v_bitop3_b32 v16, s5, -13, v191 bitop3:0xc8
	v_lshrrev_b32_e32 v0, 1, v198
	s_lshr_b32 s5, s5, 1
	v_and_b32_e32 v200, 8, v0
	s_and_b32 s5, s5, 4
	v_or3_b32 v0, v16, s5, v200
	v_and_b32_e32 v203, 15, v155
	v_lshlrev_b32_e32 v4, 3, v198
	v_lshlrev_b32_e32 v2, 8, v0
	v_ashrrev_i32_e32 v0, 4, v1
	v_and_b32_e32 v202, 24, v4
	v_bitop3_b32 v3, v0, v203, 15 bitop3:0x6c
	v_lshlrev_b32_e32 v0, 8, v0
	v_or_b32_e32 v1, 64, v1
	v_lshl_or_b32 v5, v3, 4, v0
	v_and_or_b32 v0, v155, 32, v202
	v_ashrrev_i32_e32 v3, 4, v1
	s_movk_i32 s6, 0x60
	v_lshlrev_b32_e32 v204, 1, v0
	v_bitop3_b32 v6, v3, v203, 15 bitop3:0x6c
	v_lshlrev_b32_e32 v3, 8, v3
	v_and_or_b32 v1, v1, s6, v202
	s_mov_b32 s71, 4
	v_or_b32_e32 v0, v2, v204
	v_lshl_or_b32 v148, v6, 4, v3
	v_lshl_or_b32 v2, v1, 1, v2
	s_or_b32 s7, s4, 64
	s_lshl_b32 s6, s9, 11
	s_add_i32 s70, s6, 0
	v_writelane_b32 v247, s9, 14
	s_add_i32 s6, s70, 0xc000
	v_writelane_b32 v247, s6, 15
	s_mov_b32 m0, s6
	s_add_i32 s6, s70, 0xc400
	s_add_u32 s12, s30, 0x4000
	global_load_lds_dwordx4 v5, s[30:31]
	v_writelane_b32 v247, s6, 16
	s_mov_b32 m0, s6
	s_addc_u32 s13, s31, 0
	s_add_i32 s6, s70, 0x10000
	global_load_lds_dwordx4 v148, s[30:31]
	v_writelane_b32 v247, s6, 17
	s_mov_b32 m0, s6
	s_add_i32 s6, s70, 0x10400
	global_load_lds_dwordx4 v5, s[12:13]
	s_mov_b32 m0, s6
	v_writelane_b32 v247, s6, 18
	global_load_lds_dwordx4 v148, s[12:13]
	s_mov_b32 m0, s70
	s_add_i32 s6, s70, 0x400
	global_load_lds_dwordx4 v0, s[10:11]
	s_mov_b32 m0, s6
	v_writelane_b32 v247, s6, 19
	global_load_lds_dwordx4 v2, s[10:11]
	v_mov_b32_e32 v128, v5
	v_mov_b32_e32 v149, v129
	v_mov_b32_e32 v1, v129
	v_mov_b32_e32 v3, v129
	v_lshl_add_u64 v[144:145], s[30:31], 0, v[128:129]
	v_lshl_add_u64 v[142:143], s[30:31], 0, v[148:149]
	v_lshl_add_u64 v[136:137], s[12:13], 0, v[128:129]
	v_writelane_b32 v247, s12, 20
	v_lshl_add_u64 v[140:141], s[10:11], 0, v[0:1]
	v_lshl_add_u64 v[134:135], s[10:11], 0, v[2:3]
	v_lshl_add_u64 v[138:139], s[12:13], 0, v[148:149]
	v_writelane_b32 v247, s13, 21
	v_lshlrev_b32_e32 v17, 1, v198
	s_waitcnt vmcnt(0) lgkmcnt(0)
	s_barrier
	s_and_b32 s2, s2, 0x3fffffc0
	v_lshlrev_b32_e32 v1, 4, v198
	v_and_b32_e32 v3, 32, v17
	s_movk_i32 s16, 0xc0
	v_lshrrev_b32_e32 v213, 5, v198
	s_lshl_b32 s2, s2, 2
	v_and_or_b32 v1, v1, s16, v3
	v_and_b32_e32 v3, 0x100, v4
	s_lshr_b32 s93, s7, 6
	v_lshlrev_b32_e32 v201, 2, v213
	s_add_i32 s6, s2, 0
	v_or3_b32 v1, v1, v3, v202
	s_add_i32 s6, s6, 0x18000
	s_add_u32 s66, s30, 0x8000
	s_addc_u32 s67, s31, 0
	s_add_i32 m0, s70, 0x14000
	s_add_i32 s91, s14, s7
	global_load_lds_dwordx4 v5, s[66:67]
	s_add_i32 m0, s70, 0x14400
	s_add_u32 s12, s10, 0x4000
	global_load_lds_dwordx4 v148, s[66:67]
	v_writelane_b32 v247, s10, 22
	s_addc_u32 s13, s11, 0
	s_add_i32 m0, s70, 0x4000
	v_writelane_b32 v247, s11, 23
	global_load_lds_dwordx4 v0, s[12:13]
	s_add_i32 m0, s70, 0x4400
	v_writelane_b32 v247, s12, 24
	s_add_i32 s93, s93, 4
	s_cmp_lg_u32 0, -1
	s_cselect_b32 s7, 0, 0
	s_movk_i32 s73, 0x4000
	s_mov_b32 s2, 0
	global_load_lds_dwordx4 v2, s[12:13]
	v_add_u32_e32 v192, s7, v1
	v_writelane_b32 v247, s13, 25
	v_lshlrev_b32_e32 v146, 4, v213
	v_lshlrev_b32_e32 v22, 4, v155
	v_lshlrev_b32_e32 v18, 8, v199
	v_and_b32_e32 v19, 0xf0, v22
	v_or_b32_e32 v20, 32, v146
	v_readlane_b32 s7, v247, 2
	v_bitop3_b32 v193, v146, v18, v19 bitop3:0xde
	v_bitop3_b32 v194, v20, v18, v19 bitop3:0xde
	v_or_b32_e32 v20, 64, v146
	v_add_u32_e32 v205, s7, v146
	v_add_u32_e32 v209, 0, v193
	v_bitop3_b32 v195, v20, v18, v19 bitop3:0xde
	v_or_b32_e32 v20, 0x60, v146
	ds_read_b128 v[0:3], v205 offset:128
	ds_read_b128 v[4:7], v205 offset:160
	ds_read_b128 v[8:11], v205 offset:192
	ds_read_b128 v[12:15], v205 offset:224
	v_bitop3_b32 v196, v20, v18, v19 bitop3:0xde
	ds_read_b128 v[18:21], v209 offset:57344
	v_add_u32_e32 v208, 0, v194
	s_waitcnt vmcnt(0) lgkmcnt(0)
; #define LAS __attribute__((address_space(3)))
; __device__ __forceinline__ void mask_meta(f32x16& p0, f32x16& p1) {
;     const float NEG = -__builtin_inff();
; #pragma unroll
;     for (int r = 0; r < 16; ++r) { p0[r] = NEG; if (r < 8) p1[r] = NEG; }
; }
; __device__ __forceinline__ void partialSM(f32x16& p0, f32x16& p1, float& m_reg, float& mn, float& alpha) {
;     float pmax = p0[0];
; #pragma unroll
;     for (int r = 1; r < 16; ++r) pmax = fmaxf(pmax, p0[r]);
; #pragma unroll
;     for (int r = 0; r < 16; ++r) pmax = fmaxf(pmax, p1[r]);
;     { auto rr = __builtin_amdgcn_permlane32_swap(__float_as_uint(pmax), __float_as_uint(pmax), false, false);
;       pmax = fmaxf(__uint_as_float(rr[0]), __uint_as_float(rr[1])); }
;     if (__builtin_expect(__all((pmax - m_reg) <= THR2), 1)) { mn = m_reg; alpha = 1.f; }
;     else { mn = fmaxf(m_reg, pmax); alpha = __builtin_amdgcn_exp2f(m_reg - mn); m_reg = mn; }
; #pragma unroll
;     for (int r = 0; r < 16; ++r) p0[r] = p0[r] - mn;
; #pragma unroll
;     for (int r = 0; r < 16; ++r) p1[r] = p1[r] - mn;
; #pragma unroll
;     for (int r = 0; r < 16; ++r) p0[r] = __builtin_amdgcn_exp2f(p0[r]);
; }
; __device__ __forceinline__ void qkt(f32x16& p0, f32x16& p1, const char* Kslot, int r32, int hi, const bf16x8* qr, const LAS f32x4* cp) {
; #pragma unroll
;     for (int g = 0; g < 4; ++g) { const f32x4 c0 = cp[2 * g], c1 = cp[8 + 2 * g];
; #pragma unroll
;         for (int j = 0; j < 4; ++j) { p0[4 * g + j] = c0[j]; p1[4 * g + j] = c1[j]; } }
;     const char* kb[4];
; #pragma unroll
;     for (int dd = 0; dd < 4; ++dd) kb[dd] = Kslot + KSWZ(r32, (dd * 16 + hi * 8) * 2);
; #pragma unroll
;     for (int d0 = 0; d0 < 8; ++d0) { const char* a = kb[d0 & 3] + (d0 >> 2) * 128;
;         bf16x8 b0 = *reinterpret_cast<const bf16x8*>(a);
;         bf16x8 b1 = *reinterpret_cast<const bf16x8*>(a + 32 * 256);
;         p0 = __builtin_amdgcn_mfma_f32_32x32x16_bf16(b0, qr[d0], p0, 0, 0, 0);
;         p1 = __builtin_amdgcn_mfma_f32_32x32x16_bf16(b1, qr[d0], p1, 0, 0, 0); }
; }
	v_mfma_f32_32x32x16_bf16 v[0:15], v[18:21], v[96:99], v[0:15]
	ds_read_b128 v[18:21], v208 offset:57344
	v_add_u32_e32 v207, 0, v195
	v_add_u32_e32 v206, 0, v196
	s_mov_b32 s7, 0xff800000
	s_waitcnt lgkmcnt(0)
	v_mfma_f32_32x32x16_bf16 v[0:15], v[18:21], v[100:103], v[0:15]
	ds_read_b128 v[18:21], v207 offset:57344
	s_waitcnt lgkmcnt(0)
	v_mfma_f32_32x32x16_bf16 v[0:15], v[18:21], v[104:107], v[0:15]
	ds_read_b128 v[18:21], v206 offset:57344
	s_waitcnt lgkmcnt(0)
	v_mfma_f32_32x32x16_bf16 v[0:15], v[18:21], v[108:111], v[0:15]
	v_xor_b32_e32 v249, 0x80, v209
	v_xor_b32_e32 v250, 0x80, v208
	v_xor_b32_e32 v251, 0x80, v207
	v_xor_b32_e32 v252, 0x80, v206
	ds_read_b128 v[18:21], v249 offset:57344
	s_waitcnt lgkmcnt(0)
	v_mfma_f32_32x32x16_bf16 v[0:15], v[18:21], v[112:115], v[0:15]
	ds_read_b128 v[18:21], v250 offset:57344
	s_waitcnt lgkmcnt(0)
	v_mfma_f32_32x32x16_bf16 v[0:15], v[18:21], v[116:119], v[0:15]
	ds_read_b128 v[18:21], v251 offset:57344
	s_waitcnt lgkmcnt(0)
	v_mfma_f32_32x32x16_bf16 v[0:15], v[18:21], v[120:123], v[0:15]
	ds_read_b128 v[18:21], v252 offset:57344
	s_waitcnt lgkmcnt(0)
	v_mfma_f32_32x32x16_bf16 v[0:15], v[18:21], v[124:127], v[0:15]
	s_nop 11
	v_max3_f32 v0, v8, s7, v9
	v_max3_f32 v0, v0, v10, v11
	v_max3_f32 v0, v0, v12, v13
	v_max3_f32 v0, v0, v14, v15
	v_mov_b32_e32 v1, v0
	s_nop 1
	v_permlane32_swap_b32_e32 v0, v1
	v_max_f32_e32 v1, v1, v1
	v_max_f32_e32 v0, v0, v0
	v_max_f32_e32 v0, v0, v1
	v_add_f32_e32 v1, 0x7149f2ca, v0
	v_cmp_ge_f32_e32 vcc, s33, v1
	v_max_f32_e32 v0, 0xf149f2ca, v0
	s_cmp_eq_u64 vcc, exec
	v_sub_f32_e32 v1, 0xf149f2ca, v0
	s_cselect_b64 vcc, -1, 0
	v_exp_f32_e32 v1, v1
	v_cndmask_b32_e32 v154, v0, v189, vcc
	v_mov_b32_e32 v131, v8
	v_pk_add_f32 v[64:65], v[130:131], v[154:155] op_sel_hi:[1,0] neg_lo:[0,1] neg_hi:[0,1]
	v_cndmask_b32_e64 v147, v1, 1.0, vcc
	v_exp_f32_e32 v221, v64
	v_mov_b32_e32 v0, v9
	v_mov_b32_e32 v1, v10
	v_pk_add_f32 v[66:67], v[0:1], v[154:155] op_sel_hi:[1,0] neg_lo:[0,1] neg_hi:[0,1]
	v_mov_b32_e32 v0, v11
	v_mov_b32_e32 v1, v12
	v_pk_add_f32 v[68:69], v[0:1], v[154:155] op_sel_hi:[1,0] neg_lo:[0,1] neg_hi:[0,1]
	v_mov_b32_e32 v0, v13
	v_mov_b32_e32 v1, v14
	v_sub_f32_e32 v165, v15, v154
	v_pk_add_f32 v[70:71], v[0:1], v[154:155] op_sel_hi:[1,0] neg_lo:[0,1] neg_hi:[0,1]
	s_mov_b32 s77, s14
	s_add_i32 s4, s4, s14
	s_add_i32 s3, s8, s3
	v_readlane_b32 s8, v248, 29
	v_readlane_b32 s9, v248, 30
	v_readlane_b32 s10, v248, 31
	v_readlane_b32 s11, v248, 32
	v_readlane_b32 s12, v248, 33
	v_readlane_b32 s13, v248, 34
	v_or_b32_e32 v0, s4, v199
	v_readlane_b32 s4, v247, 3
	v_readlane_b32 s14, v248, 35
	v_readlane_b32 s15, v248, 36
	s_mov_b64 s[8:9], s[12:13]
	v_sub_u32_e32 v216, v0, v201
	v_add_u32_e32 v197, s4, v146
	v_or3_b32 v0, v16, v200, s5
	v_lshlrev_b32_e32 v1, 1, v155
	s_mul_hi_i32 s4, s3, 0x104000
	s_mul_i32 s3, s3, 0x104000
	s_mov_b64 s[10:11], s[14:15]
	s_waitcnt vmcnt(4) lgkmcnt(0)
	s_barrier
	v_lshlrev_b32_e32 v0, 8, v0
	v_and_b32_e32 v211, 64, v1
	v_and_b32_e32 v210, 48, v22
	s_add_u32 s82, s10, s3
	v_bitop3_b32 v212, v17, s16, v190 bitop3:0xc8
	v_mov_b32_e32 v48, v129
	v_mov_b32_e32 v49, v129
	v_or3_b32 v150, v0, v211, v210
	s_addc_u32 s83, s11, s4
	v_or3_b32 v152, v0, v212, v210
	v_mov_b32_e32 v50, v129
	v_mov_b32_e32 v51, v129
	v_mov_b32_e32 v52, v129
	v_mov_b32_e32 v53, v129
	v_mov_b32_e32 v54, v129
	v_mov_b32_e32 v55, v129
	v_mov_b32_e32 v56, v129
	v_mov_b32_e32 v57, v129
	v_mov_b32_e32 v58, v129
	v_mov_b32_e32 v59, v129
	v_mov_b32_e32 v60, v129
	v_mov_b32_e32 v61, v129
	v_mov_b32_e32 v62, v129
	v_mov_b32_e32 v63, v129
	v_mov_b64_e32 v[32:33], v[48:49]
	v_mov_b64_e32 v[16:17], v[48:49]
	v_mov_b64_e32 v[0:1], v[48:49]
	v_lshl_add_u32 v214, v199, 2, s6
	v_add_u32_e32 v131, s6, v146
	v_mov_b32_e32 v151, v129
	v_mov_b32_e32 v153, v129
	v_mov_b32_e32 v215, 0
	s_mov_b32 s76, 0x8000
	s_movk_i32 s92, 0xbf
	s_mov_b64 s[68:69], s[82:83]
	v_mov_b32_e32 v217, v197
	v_mov_b64_e32 v[34:35], v[50:51]
	v_mov_b64_e32 v[36:37], v[52:53]
	v_mov_b64_e32 v[38:39], v[54:55]
	v_mov_b64_e32 v[40:41], v[56:57]
	v_mov_b64_e32 v[42:43], v[58:59]
	v_mov_b64_e32 v[44:45], v[60:61]
	v_mov_b64_e32 v[46:47], v[62:63]
	v_mov_b64_e32 v[18:19], v[50:51]
	v_mov_b64_e32 v[20:21], v[52:53]
	v_mov_b64_e32 v[22:23], v[54:55]
	v_mov_b64_e32 v[24:25], v[56:57]
	v_mov_b64_e32 v[26:27], v[58:59]
	v_mov_b64_e32 v[28:29], v[60:61]
	v_mov_b64_e32 v[30:31], v[62:63]
	v_mov_b64_e32 v[2:3], v[50:51]
	v_mov_b64_e32 v[4:5], v[52:53]
	v_mov_b64_e32 v[6:7], v[54:55]
	v_mov_b64_e32 v[8:9], v[56:57]
	v_mov_b64_e32 v[10:11], v[58:59]
	v_mov_b64_e32 v[12:13], v[60:61]
	v_mov_b64_e32 v[14:15], v[62:63]
	s_mov_b32 s72, 0
	v_mov_b32_e32 v236, v221
	v_mov_b32_e32 v233, v221
	v_mov_b32_e32 v235, v221
	v_mov_b32_e32 v231, v221
	v_mov_b32_e32 v234, v221
	v_mov_b32_e32 v230, v221
	v_mov_b32_e32 v232, v221
	v_mov_b32_e32 v227, v221
	v_mov_b32_e32 v229, v221
	v_mov_b32_e32 v225, v221
	v_mov_b32_e32 v228, v221
	v_mov_b32_e32 v223, v221
	v_mov_b32_e32 v226, v221
	v_mov_b32_e32 v222, v221
	v_mov_b32_e32 v224, v221
	v_mov_b32_e32 v168, v64
	v_mov_b32_e32 v169, v64
	v_mov_b32_e32 v172, v64
	v_mov_b32_e32 v173, v64
	v_mov_b32_e32 v176, v64
	v_mov_b32_e32 v177, v64
	v_mov_b32_e32 v166, v64
	v_mov_b32_e32 v167, v64
	v_mov_b32_e32 v170, v65
	v_mov_b32_e32 v171, v66
	v_mov_b32_e32 v174, v67
	v_mov_b32_e32 v175, v68
	v_mov_b32_e32 v178, v69
	v_mov_b32_e32 v179, v70
	v_mov_b32_e32 v164, v71
	v_and_b32_e32 v253, 63, v186
	v_lshrrev_b32_e32 v254, 6, v186
	v_lshlrev_b32_e32 v253, 4, v253
	v_mul_u32_u24_e32 v254, 0x800, v254
	v_add_u32_e32 v253, v253, v254
	v_add_u32_e32 v253, 0x1d000, v253
	ds_write_b128 v253, v[198:201]
	ds_write_b128 v253, v[202:205] offset:1024
	s_waitcnt lgkmcnt(0)

; #define LAS __attribute__((address_space(3)))
; __device__ __forceinline__ void finishSM(f32x16& p0, f32x16& p1, float alpha, float& l_reg, bf16x8& pa0, bf16x8& pa1, bf16x8& pa2, bf16x8& pa3) {
; #pragma unroll
;     for (int r = 0; r < 16; ++r) p1[r] = __builtin_amdgcn_exp2f(p1[r]);
;     float ps = 0;
; #pragma unroll
;     for (int r = 0; r < 16; ++r) ps += p0[r];
; #pragma unroll
;     for (int r = 0; r < 16; ++r) ps += p1[r];
;     { auto rr = __builtin_amdgcn_permlane32_swap(__float_as_uint(ps), __float_as_uint(ps), false, false);
;       ps = __uint_as_float(rr[0]) + __uint_as_float(rr[1]); }
;     l_reg = l_reg * alpha + ps;
;     ...
;     PK4(p0, 0, pa0); PK4(p0, 8, pa1); PK4(p1, 0, pa2); PK4(p1, 8, pa3);
; __device__ __forceinline__ void qkt(f32x16& p0, f32x16& p1, const char* Kslot, int r32, int hi, const bf16x8* qr, const LAS f32x4* cp) {
; #pragma unroll
;     for (int g = 0; g < 4; ++g) { const f32x4 c0 = cp[2 * g], c1 = cp[8 + 2 * g];
; #pragma unroll
;         for (int j = 0; j < 4; ++j) { p0[4 * g + j] = c0[j]; p1[4 * g + j] = c1[j]; } }
;     const char* kb[4];
; #pragma unroll
;     for (int dd = 0; dd < 4; ++dd) kb[dd] = Kslot + KSWZ(r32, (dd * 16 + hi * 8) * 2);
; #pragma unroll
;     for (int d0 = 0; d0 < 8; ++d0) { const char* a = kb[d0 & 3] + (d0 >> 2) * 128;
;         bf16x8 b0 = *reinterpret_cast<const bf16x8*>(a);
;         bf16x8 b1 = *reinterpret_cast<const bf16x8*>(a + 32 * 256);
;         p0 = __builtin_amdgcn_mfma_f32_32x32x16_bf16(b0, qr[d0], p0, 0, 0, 0);
;         p1 = __builtin_amdgcn_mfma_f32_32x32x16_bf16(b1, qr[d0], p1, 0, 0, 0); }
.LBB0_523:
	s_add_i32 s3, s70, s76
	v_lshl_add_u64 v[160:161], s[68:69], 0, v[150:151]
	v_lshl_add_u64 v[64:65], v[160:161], 0, s[84:85]
	s_mov_b32 m0, s3
	v_lshl_add_u64 v[162:163], s[68:69], 0, v[152:153]
	global_load_lds_dwordx4 v[64:65], off
	v_lshl_add_u64 v[64:65], v[162:163], 0, s[84:85]
	s_add_i32 m0, s3, 0x400
	s_nop 0
	global_load_lds_dwordx4 v[64:65], off
	s_add_i32 s3, s73, 0
	v_add_u32_e32 v218, s3, v193
	v_add_u32_e32 v219, s3, v194
	v_add_u32_e32 v220, s3, v195
	v_add_u32_e32 v237, s3, v196
	v_xor_b32_e32 v249, 0x80, v218
	v_xor_b32_e32 v250, 0x80, v219
	v_xor_b32_e32 v251, 0x80, v220
	v_xor_b32_e32 v252, 0x80, v237
	ds_read_b128 v[80:83], v217
	ds_read_b128 v[84:87], v217 offset:32
	ds_read_b128 v[64:67], v217 offset:128
	ds_read_b128 v[68:71], v217 offset:160
	ds_read_b128 v[88:91], v217 offset:64
	ds_read_b128 v[72:75], v217 offset:192
	ds_read_b128 v[92:95], v217 offset:96
	ds_read_b128 v[76:79], v217 offset:224
	ds_read_b128 v[238:241], v218 offset:49152
	ds_read_b128 v[242:245], v218 offset:57344
	ds_read_b128 v[198:201], v219 offset:49152
	ds_read_b128 v[202:205], v219 offset:57344
	s_waitcnt lgkmcnt(2)
	v_mfma_f32_32x32x16_bf16 v[80:95], v[238:241], v[96:99], v[80:95]
	v_exp_f32_e32 v173, v173
	v_exp_f32_e32 v176, v176
	v_exp_f32_e32 v177, v177
	v_exp_f32_e32 v178, v178
	v_exp_f32_e32 v179, v179
	v_exp_f32_e32 v246, v165
	v_mfma_f32_32x32x16_bf16 v[64:79], v[242:245], v[96:99], v[64:79]
	ds_read_b128 v[238:241], v220 offset:49152
	ds_read_b128 v[242:245], v220 offset:57344
	s_waitcnt lgkmcnt(2)
	v_mfma_f32_32x32x16_bf16 v[64:79], v[202:205], v[100:103], v[64:79]
	v_mfma_f32_32x32x16_bf16 v[80:95], v[198:201], v[100:103], v[80:95]
	ds_read_b128 v[198:201], v237 offset:49152
	ds_read_b128 v[202:205], v237 offset:57344
	s_waitcnt lgkmcnt(2)
	v_mfma_f32_32x32x16_bf16 v[64:79], v[242:245], v[104:107], v[64:79]
	v_mfma_f32_32x32x16_bf16 v[80:95], v[238:241], v[104:107], v[80:95]
	ds_read_b128 v[238:241], v249 offset:49152
	ds_read_b128 v[242:245], v249 offset:57344
	s_waitcnt lgkmcnt(2)
	v_mfma_f32_32x32x16_bf16 v[64:79], v[202:205], v[108:111], v[64:79]
	v_mfma_f32_32x32x16_bf16 v[80:95], v[198:201], v[108:111], v[80:95]
	ds_read_b128 v[198:201], v250 offset:49152
	ds_read_b128 v[202:205], v250 offset:57344
	s_waitcnt lgkmcnt(2)
	v_mfma_f32_32x32x16_bf16 v[64:79], v[242:245], v[112:115], v[64:79]
	v_mfma_f32_32x32x16_bf16 v[80:95], v[238:241], v[112:115], v[80:95]
	ds_read_b128 v[238:241], v251 offset:49152
	ds_read_b128 v[242:245], v251 offset:57344
	s_waitcnt lgkmcnt(2)
	v_mfma_f32_32x32x16_bf16 v[64:79], v[202:205], v[116:119], v[64:79]
	v_mfma_f32_32x32x16_bf16 v[80:95], v[198:201], v[116:119], v[80:95]
	ds_read_b128 v[198:201], v252 offset:49152
	ds_read_b128 v[202:205], v252 offset:57344
	v_exp_f32_e32 v220, v168
	s_waitcnt lgkmcnt(2)
	v_mfma_f32_32x32x16_bf16 v[64:79], v[242:245], v[120:123], v[64:79]
	v_mfma_f32_32x32x16_bf16 v[80:95], v[238:241], v[120:123], v[80:95]
	v_exp_f32_e32 v237, v169
	s_waitcnt lgkmcnt(0)
	v_mfma_f32_32x32x16_bf16 v[64:79], v[202:205], v[124:127], v[64:79]
	v_exp_f32_e32 v245, v164
	v_add_f32_e32 v164, 0, v221
	v_add_f32_e32 v164, v236, v164
	v_add_f32_e32 v164, v233, v164
	v_add_f32_e32 v164, v235, v164
	v_add_f32_e32 v164, v231, v164
	v_add_f32_e32 v164, v234, v164
	v_add_f32_e32 v164, v230, v164
	v_add_f32_e32 v164, v232, v164
	v_add_f32_e32 v164, v227, v164
	v_add_f32_e32 v164, v229, v164
	v_add_f32_e32 v164, v225, v164
	v_add_f32_e32 v164, v228, v164
	v_add_f32_e32 v164, v223, v164
	v_add_f32_e32 v164, v226, v164
	v_mfma_f32_32x32x16_bf16 v[80:95], v[198:201], v[124:127], v[80:95]
	v_exp_f32_e32 v238, v172
	v_add_f32_e32 v164, v222, v164
	v_add_f32_e32 v164, v224, v164
	v_add_f32_e32 v164, v220, v164
	v_add_f32_e32 v164, v237, v164
	v_exp_f32_e32 v239, v166
	v_add_f32_e32 v164, v238, v164
	v_exp_f32_e32 v240, v167
	v_add_f32_e32 v164, v173, v164
	v_exp_f32_e32 v241, v170
	v_add_f32_e32 v164, v176, v164
	v_exp_f32_e32 v242, v171
	v_add_f32_e32 v164, v177, v164
	v_exp_f32_e32 v243, v174
	v_add_f32_e32 v164, v239, v164
	v_exp_f32_e32 v244, v175
	v_add_f32_e32 v164, v240, v164
	v_add_f32_e32 v164, v241, v164
	v_add_f32_e32 v164, v242, v164
	v_add_f32_e32 v164, v243, v164
	v_add_f32_e32 v164, v244, v164
	v_add_f32_e32 v164, v178, v164
	v_add_f32_e32 v164, v179, v164
	v_add_f32_e32 v164, v245, v164
	v_add_f32_e32 v218, v246, v164
	v_mov_b32_e32 v219, v218
	s_nop 1
	v_permlane32_swap_b32_e32 v218, v219
	v_cvt_pk_bf16_f32 v164, v221, v236
	v_cvt_pk_bf16_f32 v165, v233, v235
	v_cvt_pk_bf16_f32 v166, v231, v234
	v_cvt_pk_bf16_f32 v167, v230, v232
	v_cvt_pk_bf16_f32 v168, v227, v229
	v_cvt_pk_bf16_f32 v169, v225, v228
	v_cvt_pk_bf16_f32 v170, v223, v226
	v_cvt_pk_bf16_f32 v171, v222, v224
	v_cvt_pk_bf16_f32 v172, v220, v237
	v_cvt_pk_bf16_f32 v173, v238, v173
	v_cvt_pk_bf16_f32 v174, v176, v177
	v_cvt_pk_bf16_f32 v175, v239, v240
	v_cvt_pk_bf16_f32 v176, v241, v242
	v_cvt_pk_bf16_f32 v177, v243, v244
	v_cvt_pk_bf16_f32 v178, v178, v179
	v_cvt_pk_bf16_f32 v179, v245, v246
	s_nop 0
	v_permlane32_swap_b32_e32 v164, v166
	v_permlane32_swap_b32_e32 v165, v167
	v_permlane32_swap_b32_e32 v168, v170
	v_permlane32_swap_b32_e32 v169, v171
	v_permlane32_swap_b32_e32 v172, v174
	v_permlane32_swap_b32_e32 v173, v175
	v_permlane32_swap_b32_e32 v176, v178
	v_permlane32_swap_b32_e32 v177, v179
	v_add_u32_e32 v236, s2, v192
	ds_read_b64_tr_b16 v[220:221], v236 offset:0
	ds_read_b64_tr_b16 v[222:223], v236 offset:0x800
	ds_read_b64_tr_b16 v[224:225], v236 offset:0x1000
	ds_read_b64_tr_b16 v[226:227], v236 offset:0x1800
	ds_read_b64_tr_b16 v[228:229], v236 offset:0x2000
	ds_read_b64_tr_b16 v[230:231], v236 offset:0x2800
	ds_read_b64_tr_b16 v[232:233], v236 offset:0x3000
	ds_read_b64_tr_b16 v[234:235], v236 offset:0x3800
	s_waitcnt lgkmcnt(4)
; #define SBAR() __builtin_amdgcn_sched_barrier(0)
; #define PV_RD(d0, kh, X) do { constexpr int b_ = v_rd_off(d0, 2 * (kh), 0); TRRD(X##l0, b_); TRRD(X##h0, b_ + 2048); TRRD(X##l1, b_ + 4096); TRRD(X##h1, b_ + 6144); } while (0)
; #define PV_MM(d0, X, PA, PB) do { \
;         o[d0] = __builtin_amdgcn_mfma_f32_32x32x16_bf16(PA, (bf16x8){X##l0[0], X##l0[1], X##l0[2], X##l0[3], X##h0[0], X##h0[1], X##h0[2], X##h0[3]}, o[d0], 0, 0, 0);   \
;         o[d0] = __builtin_amdgcn_mfma_f32_32x32x16_bf16(PB, (bf16x8){X##l1[0], X##l1[1], X##l1[2], X##l1[3], X##h1[0], X##h1[1], X##h1[2], X##h1[3]}, o[d0], 0, 0, 0); } while (0)
; #define PV_W4() do { asm volatile("s_waitcnt lgkmcnt(4)" ::: "memory"); SBAR(); } while (0)
; #define PV_W0() do { asm volatile("s_waitcnt lgkmcnt(0)" ::: "memory"); SBAR(); } while (0)
; __device__ __forceinline__ void mask_tile(f32x16& p0, f32x16& p1, int dq) {
;     const float NEG = -__builtin_inff();
; #pragma unroll
;     for (int r = 0; r < 16; ++r) { const int c = (r & 3) + 8 * (r >> 2); if (dq - c < 0) p0[r] = NEG; if (dq - c - 32 < 0) p1[r] = NEG; }
; }
; __device__ __forceinline__ void pv_tile(f32x16* o, int vb0, bf16x8 pa0, bf16x8 pa1, bf16x8 pa2, bf16x8 pa3) {
;     ...
;     s16x4 al0, al1, ah0, ah1, bl0, bl1, bh0, bh1;
;     PV_RD(0, 0, a);
;     PV_RD(0, 1, b); PV_W4(); PV_MM(0, a, pa0, pa1); SBAR();
;     PV_RD(1, 0, a); PV_W4(); PV_MM(0, b, pa2, pa3); SBAR();
;     PV_RD(1, 1, b); PV_W4(); PV_MM(1, a, pa0, pa1); SBAR();
;     PV_RD(2, 0, a); PV_W4(); PV_MM(1, b, pa2, pa3); SBAR();
;     PV_RD(2, 1, b); PV_W4(); PV_MM(2, a, pa0, pa1); SBAR();
;     PV_RD(3, 0, a); PV_W4(); PV_MM(2, b, pa2, pa3); SBAR();
;     PV_RD(3, 1, b); PV_W4(); PV_MM(3, a, pa0, pa1); SBAR();
;     PV_W0(); PV_MM(3, b, pa2, pa3);
	s_nop 0
	v_mfma_f32_32x32x16_bf16 v[48:63], v[164:167], v[220:223], v[48:63]
	v_mfma_f32_32x32x16_bf16 v[48:63], v[168:171], v[224:227], v[48:63]
	ds_read_b64_tr_b16 v[220:221], v236 offset:0x200
	ds_read_b64_tr_b16 v[222:223], v236 offset:0xa00
	ds_read_b64_tr_b16 v[224:225], v236 offset:0x1200
	ds_read_b64_tr_b16 v[226:227], v236 offset:0x1a00
	s_waitcnt lgkmcnt(4)
	v_mfma_f32_32x32x16_bf16 v[48:63], v[172:175], v[228:231], v[48:63]
	v_mfma_f32_32x32x16_bf16 v[48:63], v[176:179], v[232:235], v[48:63]
	ds_read_b64_tr_b16 v[228:229], v236 offset:0x2200
	ds_read_b64_tr_b16 v[230:231], v236 offset:0x2a00
	ds_read_b64_tr_b16 v[232:233], v236 offset:0x3200
	ds_read_b64_tr_b16 v[234:235], v236 offset:0x3a00
	s_waitcnt lgkmcnt(4)
	v_mfma_f32_32x32x16_bf16 v[32:47], v[164:167], v[220:223], v[32:47]
	v_mfma_f32_32x32x16_bf16 v[32:47], v[168:171], v[224:227], v[32:47]
	ds_read_b64_tr_b16 v[220:221], v236 offset:0x400
	ds_read_b64_tr_b16 v[222:223], v236 offset:0xc00
	ds_read_b64_tr_b16 v[224:225], v236 offset:0x1400
	ds_read_b64_tr_b16 v[226:227], v236 offset:0x1c00
	s_waitcnt lgkmcnt(4)
	v_mfma_f32_32x32x16_bf16 v[32:47], v[172:175], v[228:231], v[32:47]
	v_mfma_f32_32x32x16_bf16 v[32:47], v[176:179], v[232:235], v[32:47]
	ds_read_b64_tr_b16 v[228:229], v236 offset:0x2400
	ds_read_b64_tr_b16 v[230:231], v236 offset:0x2c00
	ds_read_b64_tr_b16 v[232:233], v236 offset:0x3400
	ds_read_b64_tr_b16 v[234:235], v236 offset:0x3c00
	s_waitcnt lgkmcnt(4)
	v_mfma_f32_32x32x16_bf16 v[16:31], v[164:167], v[220:223], v[16:31]
	v_mfma_f32_32x32x16_bf16 v[16:31], v[168:171], v[224:227], v[16:31]
	ds_read_b64_tr_b16 v[220:221], v236 offset:0x600
	ds_read_b64_tr_b16 v[222:223], v236 offset:0xe00
	ds_read_b64_tr_b16 v[224:225], v236 offset:0x1600
	ds_read_b64_tr_b16 v[226:227], v236 offset:0x1e00
	s_waitcnt lgkmcnt(4)
	v_mfma_f32_32x32x16_bf16 v[16:31], v[172:175], v[228:231], v[16:31]
	v_mfma_f32_32x32x16_bf16 v[16:31], v[176:179], v[232:235], v[16:31]
	ds_read_b64_tr_b16 v[228:229], v236 offset:0x2600
	ds_read_b64_tr_b16 v[230:231], v236 offset:0x2e00
	ds_read_b64_tr_b16 v[232:233], v236 offset:0x3600
	ds_read_b64_tr_b16 v[234:235], v236 offset:0x3e00
	s_waitcnt lgkmcnt(4)
	v_mfma_f32_32x32x16_bf16 v[0:15], v[164:167], v[220:223], v[0:15]
	v_mfma_f32_32x32x16_bf16 v[0:15], v[168:171], v[224:227], v[0:15]
	s_waitcnt lgkmcnt(0)
	v_mfma_f32_32x32x16_bf16 v[0:15], v[172:175], v[228:231], v[0:15]
	s_sub_i32 s2, s92, 64
	s_cmp_le_i32 s2, s91
	v_mfma_f32_32x32x16_bf16 v[0:15], v[176:179], v[232:235], v[0:15]
	s_cbranch_scc1 .LBB0_525
	v_cmp_gt_i32_e64 s[62:63], 26, v216
	v_cmp_gt_i32_e64 s[64:65], 27, v216
	v_cmp_gt_i32_e64 s[60:61], 25, v216
	s_and_b64 s[62:63], s[64:65], s[62:63]
	v_cmp_gt_i32_e64 s[58:59], 24, v216
	s_and_b64 s[60:61], s[62:63], s[60:61]
	v_cmp_gt_i32_e64 s[56:57], 19, v216
	s_and_b64 s[58:59], s[60:61], s[58:59]
	v_cmp_gt_i32_e64 s[54:55], 18, v216
	s_and_b64 s[56:57], s[58:59], s[56:57]
	v_cmp_gt_i32_e64 s[52:53], 17, v216
	s_and_b64 s[54:55], s[56:57], s[54:55]
	v_cmp_gt_i32_e64 s[50:51], 16, v216
	s_and_b64 s[52:53], s[54:55], s[52:53]
	v_cmp_gt_i32_e64 s[48:49], 11, v216
	s_and_b64 s[50:51], s[52:53], s[50:51]
	v_cmp_gt_i32_e64 s[46:47], 10, v216
	s_and_b64 s[48:49], s[50:51], s[48:49]
	v_cmp_gt_i32_e64 s[44:45], 9, v216
	s_and_b64 s[46:47], s[48:49], s[46:47]
	v_cmp_gt_i32_e64 s[42:43], 8, v216
	s_and_b64 s[44:45], s[46:47], s[44:45]
	v_cmp_gt_i32_e64 s[40:41], 3, v216
	s_and_b64 s[42:43], s[44:45], s[42:43]
	v_cmp_gt_i32_e64 s[38:39], 2, v216
	s_and_b64 s[40:41], s[42:43], s[40:41]
	v_cmp_gt_i32_e64 s[36:37], 1, v216
	s_and_b64 s[38:39], s[40:41], s[38:39]
	v_cmp_gt_i32_e64 s[34:35], 0, v216
	s_and_b64 s[36:37], s[38:39], s[36:37]
	s_and_b64 s[34:35], s[36:37], s[34:35]
	v_cmp_gt_i32_e64 s[28:29], 58, v216
	v_cndmask_b32_e64 v80, v80, v130, s[34:35]
	v_cmp_gt_i32_e64 s[34:35], 59, v216
	v_cmp_gt_i32_e64 s[26:27], 57, v216
	s_and_b64 s[28:29], s[34:35], s[28:29]
	v_cmp_gt_i32_e64 s[24:25], 56, v216
	s_and_b64 s[26:27], s[28:29], s[26:27]
	v_cmp_gt_i32_e64 s[22:23], 51, v216
	s_and_b64 s[24:25], s[26:27], s[24:25]
	v_cmp_gt_i32_e64 s[20:21], 50, v216
	s_and_b64 s[22:23], s[24:25], s[22:23]
	v_cmp_gt_i32_e64 s[18:19], 49, v216
	s_and_b64 s[20:21], s[22:23], s[20:21]
	v_cmp_gt_i32_e64 s[16:17], 48, v216
	s_and_b64 s[18:19], s[20:21], s[18:19]
	v_cmp_gt_i32_e64 s[14:15], 43, v216
	s_and_b64 s[16:17], s[18:19], s[16:17]
	v_cmp_gt_i32_e64 s[12:13], 42, v216
	s_and_b64 s[14:15], s[16:17], s[14:15]
	v_cmp_gt_i32_e64 s[10:11], 41, v216
	s_and_b64 s[12:13], s[14:15], s[12:13]
	v_cmp_gt_i32_e64 s[8:9], 40, v216
	s_and_b64 s[10:11], s[12:13], s[10:11]
	v_cmp_gt_i32_e64 s[6:7], 35, v216
	s_and_b64 s[8:9], s[10:11], s[8:9]
	v_cmp_gt_i32_e64 s[4:5], 34, v216
	s_and_b64 s[6:7], s[8:9], s[6:7]
	v_cmp_gt_i32_e64 s[2:3], 33, v216
	s_and_b64 s[4:5], s[6:7], s[4:5]
	v_cmp_gt_i32_e32 vcc, 32, v216
	s_and_b64 s[2:3], s[4:5], s[2:3]
	s_and_b64 vcc, s[2:3], vcc
	v_cndmask_b32_e64 v95, v95, v130, s[64:65]
	v_cndmask_b32_e64 v94, v94, v130, s[62:63]
	v_cndmask_b32_e64 v93, v93, v130, s[60:61]
	v_cndmask_b32_e64 v92, v92, v130, s[58:59]
	v_cndmask_b32_e64 v91, v91, v130, s[56:57]
	v_cndmask_b32_e64 v90, v90, v130, s[54:55]
	v_cndmask_b32_e64 v89, v89, v130, s[52:53]
	v_cndmask_b32_e64 v88, v88, v130, s[50:51]
	v_cndmask_b32_e64 v87, v87, v130, s[48:49]
	v_cndmask_b32_e64 v86, v86, v130, s[46:47]
	v_cndmask_b32_e64 v85, v85, v130, s[44:45]
	v_cndmask_b32_e64 v84, v84, v130, s[42:43]
	v_cndmask_b32_e64 v83, v83, v130, s[40:41]
	v_cndmask_b32_e64 v82, v82, v130, s[38:39]
	v_cndmask_b32_e64 v81, v81, v130, s[36:37]
	v_cndmask_b32_e64 v79, v79, v130, s[34:35]
	v_cndmask_b32_e64 v78, v78, v130, s[28:29]
	v_cndmask_b32_e64 v77, v77, v130, s[26:27]
	v_cndmask_b32_e64 v76, v76, v130, s[24:25]
	v_cndmask_b32_e64 v75, v75, v130, s[22:23]
	v_cndmask_b32_e64 v74, v74, v130, s[20:21]
	v_cndmask_b32_e64 v73, v73, v130, s[18:19]
	v_cndmask_b32_e64 v72, v72, v130, s[16:17]
	v_cndmask_b32_e64 v71, v71, v130, s[14:15]
	v_cndmask_b32_e64 v70, v70, v130, s[12:13]
	v_cndmask_b32_e64 v69, v69, v130, s[10:11]
	v_cndmask_b32_e64 v68, v68, v130, s[8:9]
	v_cndmask_b32_e64 v67, v67, v130, s[6:7]
	v_cndmask_b32_e64 v66, v66, v130, s[4:5]
	v_cndmask_b32_e64 v65, v65, v130, s[2:3]
	v_cndmask_b32_e32 v64, v64, v130, vcc

; #define LAS __attribute__((address_space(3)))
; __device__ __forceinline__ void partialSM(f32x16& p0, f32x16& p1, float& m_reg, float& mn, float& alpha) {
;     ...
; #pragma unroll
;     for (int r = 0; r < 16; ++r) p0[r] = p0[r] - mn;
; #pragma unroll
;     for (int r = 0; r < 16; ++r) p1[r] = p1[r] - mn;
; #pragma unroll
;     for (int r = 0; r < 16; ++r) p0[r] = __builtin_amdgcn_exp2f(p0[r]);
; __device__ __forceinline__ void finishSM(f32x16& p0, f32x16& p1, float alpha, float& l_reg, bf16x8& pa0, bf16x8& pa1, bf16x8& pa2, bf16x8& pa3) {
; #pragma unroll
;     for (int r = 0; r < 16; ++r) p1[r] = __builtin_amdgcn_exp2f(p1[r]);
;     float ps = 0;
; #pragma unroll
;     for (int r = 0; r < 16; ++r) ps += p0[r];
; #pragma unroll
;     for (int r = 0; r < 16; ++r) ps += p1[r];
;     { auto rr = __builtin_amdgcn_permlane32_swap(__float_as_uint(ps), __float_as_uint(ps), false, false);
;       ps = __uint_as_float(rr[0]) + __uint_as_float(rr[1]); }
;     l_reg = l_reg * alpha + ps;
;     ...
;     PK4(p0, 0, pa0); PK4(p0, 8, pa1); PK4(p1, 0, pa2); PK4(p1, 8, pa3);
; __device__ __forceinline__ void qkt(f32x16& p0, f32x16& p1, const char* Kslot, int r32, int hi, const bf16x8* qr, const LAS f32x4* cp) {
; #pragma unroll
;     for (int g = 0; g < 4; ++g) { const f32x4 c0 = cp[2 * g], c1 = cp[8 + 2 * g];
; #pragma unroll
;         for (int j = 0; j < 4; ++j) { p0[4 * g + j] = c0[j]; p1[4 * g + j] = c1[j]; } }
;     const char* kb[4];
; #pragma unroll
;     for (int dd = 0; dd < 4; ++dd) kb[dd] = Kslot + KSWZ(r32, (dd * 16 + hi * 8) * 2);
; #pragma unroll
;     for (int d0 = 0; d0 < 8; ++d0) { const char* a = kb[d0 & 3] + (d0 >> 2) * 128;
;         bf16x8 b0 = *reinterpret_cast<const bf16x8*>(a);
;         bf16x8 b1 = *reinterpret_cast<const bf16x8*>(a + 32 * 256);
;         p0 = __builtin_amdgcn_mfma_f32_32x32x16_bf16(b0, qr[d0], p0, 0, 0, 0);
;         p1 = __builtin_amdgcn_mfma_f32_32x32x16_bf16(b1, qr[d0], p1, 0, 0, 0); }
.LBB0_537:
	v_cndmask_b32_e64 v154, v164, v154, s[2:3]
	v_sub_f32_e32 v80, v80, v154
	v_sub_f32_e32 v81, v81, v154
	v_sub_f32_e32 v82, v82, v154
	v_sub_f32_e32 v83, v83, v154
	v_sub_f32_e32 v84, v84, v154
	v_sub_f32_e32 v85, v85, v154
	v_sub_f32_e32 v86, v86, v154
	v_sub_f32_e32 v87, v87, v154
	v_sub_f32_e32 v88, v88, v154
	v_sub_f32_e32 v89, v89, v154
	v_sub_f32_e32 v90, v90, v154
	v_sub_f32_e32 v91, v91, v154
	v_sub_f32_e32 v92, v92, v154
	v_sub_f32_e32 v93, v93, v154
	v_sub_f32_e32 v94, v94, v154
	v_sub_f32_e32 v95, v95, v154
	v_sub_f32_e32 v164, v64, v154
	v_sub_f32_e32 v165, v65, v154
	v_sub_f32_e32 v166, v66, v154
	v_sub_f32_e32 v167, v67, v154
	v_sub_f32_e32 v168, v68, v154
	v_sub_f32_e32 v169, v69, v154
	v_sub_f32_e32 v170, v70, v154
	v_sub_f32_e32 v171, v71, v154
	v_sub_f32_e32 v172, v72, v154
	v_sub_f32_e32 v173, v73, v154
	v_sub_f32_e32 v174, v74, v154
	v_sub_f32_e32 v175, v75, v154
	v_sub_f32_e32 v176, v76, v154
	v_exp_f32_e32 v177, v80
	v_exp_f32_e32 v178, v81
	v_exp_f32_e32 v179, v82
	v_exp_f32_e32 v221, v83
	v_exp_f32_e32 v222, v84
	v_exp_f32_e32 v223, v85
	v_exp_f32_e32 v224, v86
	v_exp_f32_e32 v225, v87
	v_exp_f32_e32 v226, v88
	v_exp_f32_e32 v227, v89
	v_exp_f32_e32 v228, v90
	v_exp_f32_e32 v229, v91
	v_exp_f32_e32 v230, v92
	v_exp_f32_e32 v231, v93
	v_exp_f32_e32 v232, v94
	v_exp_f32_e32 v233, v95
	v_sub_f32_e32 v234, v77, v154
	v_sub_f32_e32 v235, v78, v154
	v_sub_f32_e32 v236, v79, v154
	s_add_i32 s2, s76, 0
	v_add_u32_e32 v237, s2, v193
	v_add_u32_e32 v238, s2, v194
	v_add_u32_e32 v239, s2, v195
	v_add_u32_e32 v240, s2, v196
	v_xor_b32_e32 v249, 0x80, v237
	v_xor_b32_e32 v250, 0x80, v238
	v_xor_b32_e32 v251, 0x80, v239
	v_xor_b32_e32 v252, 0x80, v240
	ds_read_b128 v[80:83], v217 offset:256
	ds_read_b128 v[84:87], v217 offset:288
	ds_read_b128 v[64:67], v217 offset:384
	ds_read_b128 v[68:71], v217 offset:416
	ds_read_b128 v[88:91], v217 offset:320
	ds_read_b128 v[72:75], v217 offset:448
	ds_read_b128 v[92:95], v217 offset:352
	ds_read_b128 v[76:79], v217 offset:480
	ds_read_b128 v[156:159], v237 offset:49152
	ds_read_b128 v[160:163], v237 offset:57344
	ds_read_b128 v[198:201], v238 offset:49152
	ds_read_b128 v[202:205], v238 offset:57344
	s_waitcnt lgkmcnt(2)
	v_mfma_f32_32x32x16_bf16 v[80:95], v[156:159], v[96:99], v[80:95]
	v_exp_f32_e32 v167, v167
	v_exp_f32_e32 v168, v168
	v_exp_f32_e32 v169, v169
	v_exp_f32_e32 v170, v170
	v_exp_f32_e32 v171, v171
	v_exp_f32_e32 v172, v172
	v_mfma_f32_32x32x16_bf16 v[64:79], v[160:163], v[96:99], v[64:79]
	ds_read_b128 v[156:159], v239 offset:49152
	ds_read_b128 v[160:163], v239 offset:57344
	v_exp_f32_e32 v173, v173
	v_exp_f32_e32 v174, v174
	v_exp_f32_e32 v175, v175
	v_exp_f32_e32 v176, v176
	v_exp_f32_e32 v234, v234
	v_exp_f32_e32 v235, v235
	s_waitcnt lgkmcnt(2)
	v_mfma_f32_32x32x16_bf16 v[80:95], v[198:201], v[100:103], v[80:95]
	v_exp_f32_e32 v236, v236
	v_mfma_f32_32x32x16_bf16 v[64:79], v[202:205], v[100:103], v[64:79]
	ds_read_b128 v[198:201], v240 offset:49152
	ds_read_b128 v[202:205], v240 offset:57344
	s_waitcnt lgkmcnt(2)
	v_mfma_f32_32x32x16_bf16 v[80:95], v[156:159], v[104:107], v[80:95]
	v_mfma_f32_32x32x16_bf16 v[64:79], v[160:163], v[104:107], v[64:79]
	ds_read_b128 v[156:159], v249 offset:49152
	ds_read_b128 v[160:163], v249 offset:57344
	s_waitcnt lgkmcnt(2)
	v_mfma_f32_32x32x16_bf16 v[80:95], v[198:201], v[108:111], v[80:95]
	v_mfma_f32_32x32x16_bf16 v[64:79], v[202:205], v[108:111], v[64:79]
	ds_read_b128 v[198:201], v250 offset:49152
	ds_read_b128 v[202:205], v250 offset:57344
	v_exp_f32_e32 v237, v164
	s_waitcnt lgkmcnt(2)
	v_mfma_f32_32x32x16_bf16 v[80:95], v[156:159], v[112:115], v[80:95]
	v_mfma_f32_32x32x16_bf16 v[64:79], v[160:163], v[112:115], v[64:79]
	ds_read_b128 v[156:159], v251 offset:49152
	ds_read_b128 v[160:163], v251 offset:57344
	v_exp_f32_e32 v238, v165
	s_waitcnt lgkmcnt(2)
	v_mfma_f32_32x32x16_bf16 v[80:95], v[198:201], v[116:119], v[80:95]
	v_mfma_f32_32x32x16_bf16 v[64:79], v[202:205], v[116:119], v[64:79]
	ds_read_b128 v[198:201], v252 offset:49152
	ds_read_b128 v[202:205], v252 offset:57344
	v_exp_f32_e32 v239, v166
	s_waitcnt lgkmcnt(2)
	v_mfma_f32_32x32x16_bf16 v[80:95], v[156:159], v[120:123], v[80:95]
	v_mfma_f32_32x32x16_bf16 v[64:79], v[160:163], v[120:123], v[64:79]
	s_waitcnt lgkmcnt(0)
	v_mfma_f32_32x32x16_bf16 v[80:95], v[198:201], v[124:127], v[80:95]
	v_add_f32_e32 v156, 0, v177
	v_add_f32_e32 v156, v178, v156
	v_add_f32_e32 v156, v179, v156
	v_add_f32_e32 v156, v221, v156
	v_add_f32_e32 v156, v222, v156
	v_add_f32_e32 v156, v223, v156
	v_add_f32_e32 v156, v224, v156
	v_add_f32_e32 v156, v225, v156
	v_add_f32_e32 v156, v226, v156
	v_add_f32_e32 v156, v227, v156
	v_add_f32_e32 v156, v228, v156
	v_add_f32_e32 v156, v229, v156
	v_add_f32_e32 v156, v230, v156
	v_add_f32_e32 v156, v231, v156
	v_add_f32_e32 v156, v232, v156
	v_add_f32_e32 v156, v233, v156
	v_add_f32_e32 v156, v237, v156
	v_add_f32_e32 v156, v238, v156
	v_add_f32_e32 v156, v239, v156
	v_add_f32_e32 v156, v167, v156
	v_add_f32_e32 v156, v168, v156
	v_add_f32_e32 v156, v169, v156
	v_add_f32_e32 v156, v170, v156
	v_add_f32_e32 v156, v171, v156
	v_add_f32_e32 v156, v172, v156
	v_add_f32_e32 v156, v173, v156
	v_mfma_f32_32x32x16_bf16 v[64:79], v[202:205], v[124:127], v[64:79]
	v_add_f32_e32 v156, v174, v156
	v_add_f32_e32 v156, v175, v156
	v_add_f32_e32 v156, v176, v156
	v_add_f32_e32 v156, v234, v156
	v_add_f32_e32 v156, v235, v156
	v_add_f32_e32 v156, v236, v156
	v_mov_b32_e32 v157, v156
	s_nop 1
	v_permlane32_swap_b32_e32 v156, v157
	v_cvt_pk_bf16_f32 v158, v177, v178
	v_cvt_pk_bf16_f32 v159, v179, v221
	v_cvt_pk_bf16_f32 v160, v222, v223
	v_cvt_pk_bf16_f32 v161, v224, v225
	v_cvt_pk_bf16_f32 v162, v226, v227
	v_cvt_pk_bf16_f32 v163, v228, v229
	v_cvt_pk_bf16_f32 v164, v230, v231
	v_cvt_pk_bf16_f32 v165, v232, v233
	v_cvt_pk_bf16_f32 v166, v237, v238
	v_cvt_pk_bf16_f32 v167, v239, v167
	v_cvt_pk_bf16_f32 v168, v168, v169
	v_cvt_pk_bf16_f32 v169, v170, v171
	v_cvt_pk_bf16_f32 v170, v172, v173
	v_cvt_pk_bf16_f32 v171, v174, v175
	v_cvt_pk_bf16_f32 v172, v176, v234
	v_cvt_pk_bf16_f32 v173, v235, v236
	s_nop 0
	v_permlane32_swap_b32_e32 v158, v160
	v_permlane32_swap_b32_e32 v159, v161
	v_permlane32_swap_b32_e32 v162, v164
	v_permlane32_swap_b32_e32 v163, v165
	v_permlane32_swap_b32_e32 v166, v168
	v_permlane32_swap_b32_e32 v167, v169
	v_permlane32_swap_b32_e32 v170, v172
	v_permlane32_swap_b32_e32 v171, v173
	v_add_u32_e32 v178, s73, v192
	ds_read_b64_tr_b16 v[174:175], v178 offset:0
	ds_read_b64_tr_b16 v[176:177], v178 offset:0x800
	ds_read_b64_tr_b16 v[222:223], v178 offset:0x1000
	ds_read_b64_tr_b16 v[224:225], v178 offset:0x1800
	ds_read_b64_tr_b16 v[226:227], v178 offset:0x2000
	ds_read_b64_tr_b16 v[228:229], v178 offset:0x2800
	ds_read_b64_tr_b16 v[230:231], v178 offset:0x3000
	ds_read_b64_tr_b16 v[232:233], v178 offset:0x3800
	s_waitcnt lgkmcnt(4)
; #define SBAR() __builtin_amdgcn_sched_barrier(0)
; #define PV_RD(d0, kh, X) do { constexpr int b_ = v_rd_off(d0, 2 * (kh), 0); TRRD(X##l0, b_); TRRD(X##h0, b_ + 2048); TRRD(X##l1, b_ + 4096); TRRD(X##h1, b_ + 6144); } while (0)
; #define PV_MM(d0, X, PA, PB) do { \
;         o[d0] = __builtin_amdgcn_mfma_f32_32x32x16_bf16(PA, (bf16x8){X##l0[0], X##l0[1], X##l0[2], X##l0[3], X##h0[0], X##h0[1], X##h0[2], X##h0[3]}, o[d0], 0, 0, 0);   \
;         o[d0] = __builtin_amdgcn_mfma_f32_32x32x16_bf16(PB, (bf16x8){X##l1[0], X##l1[1], X##l1[2], X##l1[3], X##h1[0], X##h1[1], X##h1[2], X##h1[3]}, o[d0], 0, 0, 0); } while (0)
; #define PV_W4() do { asm volatile("s_waitcnt lgkmcnt(4)" ::: "memory"); SBAR(); } while (0)
; #define PV_W0() do { asm volatile("s_waitcnt lgkmcnt(0)" ::: "memory"); SBAR(); } while (0)
; __device__ __forceinline__ void mask_tile(f32x16& p0, f32x16& p1, int dq) {
;     const float NEG = -__builtin_inff();
; #pragma unroll
;     for (int r = 0; r < 16; ++r) { const int c = (r & 3) + 8 * (r >> 2); if (dq - c < 0) p0[r] = NEG; if (dq - c - 32 < 0) p1[r] = NEG; }
; }
; __device__ __forceinline__ void pv_tile(f32x16* o, int vb0, bf16x8 pa0, bf16x8 pa1, bf16x8 pa2, bf16x8 pa3) {
;     ...
;     s16x4 al0, al1, ah0, ah1, bl0, bl1, bh0, bh1;
;     PV_RD(0, 0, a);
;     PV_RD(0, 1, b); PV_W4(); PV_MM(0, a, pa0, pa1); SBAR();
;     PV_RD(1, 0, a); PV_W4(); PV_MM(0, b, pa2, pa3); SBAR();
;     PV_RD(1, 1, b); PV_W4(); PV_MM(1, a, pa0, pa1); SBAR();
;     PV_RD(2, 0, a); PV_W4(); PV_MM(1, b, pa2, pa3); SBAR();
;     PV_RD(2, 1, b); PV_W4(); PV_MM(2, a, pa0, pa1); SBAR();
;     PV_RD(3, 0, a); PV_W4(); PV_MM(2, b, pa2, pa3); SBAR();
;     PV_RD(3, 1, b); PV_W4(); PV_MM(3, a, pa0, pa1); SBAR();
;     PV_W0(); PV_MM(3, b, pa2, pa3);
	s_nop 0
	v_mfma_f32_32x32x16_bf16 v[48:63], v[158:161], v[174:177], v[48:63]
	v_mfma_f32_32x32x16_bf16 v[48:63], v[162:165], v[222:225], v[48:63]
	ds_read_b64_tr_b16 v[174:175], v178 offset:0x200
	ds_read_b64_tr_b16 v[176:177], v178 offset:0xa00
	ds_read_b64_tr_b16 v[222:223], v178 offset:0x1200
	ds_read_b64_tr_b16 v[224:225], v178 offset:0x1a00
	s_waitcnt lgkmcnt(4)
	v_mfma_f32_32x32x16_bf16 v[48:63], v[166:169], v[226:229], v[48:63]
	v_mfma_f32_32x32x16_bf16 v[48:63], v[170:173], v[230:233], v[48:63]
	ds_read_b64_tr_b16 v[226:227], v178 offset:0x2200
	ds_read_b64_tr_b16 v[228:229], v178 offset:0x2a00
	ds_read_b64_tr_b16 v[230:231], v178 offset:0x3200
	ds_read_b64_tr_b16 v[232:233], v178 offset:0x3a00
	s_waitcnt lgkmcnt(4)
	v_mfma_f32_32x32x16_bf16 v[32:47], v[158:161], v[174:177], v[32:47]
	v_mfma_f32_32x32x16_bf16 v[32:47], v[162:165], v[222:225], v[32:47]
	ds_read_b64_tr_b16 v[174:175], v178 offset:0x400
	ds_read_b64_tr_b16 v[176:177], v178 offset:0xc00
	ds_read_b64_tr_b16 v[222:223], v178 offset:0x1400
	ds_read_b64_tr_b16 v[224:225], v178 offset:0x1c00
	s_waitcnt lgkmcnt(4)
	v_mfma_f32_32x32x16_bf16 v[32:47], v[166:169], v[226:229], v[32:47]
	v_mfma_f32_32x32x16_bf16 v[32:47], v[170:173], v[230:233], v[32:47]
	ds_read_b64_tr_b16 v[226:227], v178 offset:0x2400
	ds_read_b64_tr_b16 v[228:229], v178 offset:0x2c00
	ds_read_b64_tr_b16 v[230:231], v178 offset:0x3400
	ds_read_b64_tr_b16 v[232:233], v178 offset:0x3c00
	s_waitcnt lgkmcnt(4)
	v_mfma_f32_32x32x16_bf16 v[16:31], v[158:161], v[174:177], v[16:31]
	v_mfma_f32_32x32x16_bf16 v[16:31], v[162:165], v[222:225], v[16:31]
	ds_read_b64_tr_b16 v[174:175], v178 offset:0x600
	ds_read_b64_tr_b16 v[176:177], v178 offset:0xe00
	ds_read_b64_tr_b16 v[222:223], v178 offset:0x1600
	ds_read_b64_tr_b16 v[224:225], v178 offset:0x1e00
	s_waitcnt lgkmcnt(4)
	v_mfma_f32_32x32x16_bf16 v[16:31], v[166:169], v[226:229], v[16:31]
	v_mfma_f32_32x32x16_bf16 v[16:31], v[170:173], v[230:233], v[16:31]
	ds_read_b64_tr_b16 v[226:227], v178 offset:0x2600
	ds_read_b64_tr_b16 v[228:229], v178 offset:0x2e00
	ds_read_b64_tr_b16 v[230:231], v178 offset:0x3600
	ds_read_b64_tr_b16 v[232:233], v178 offset:0x3e00
	s_waitcnt lgkmcnt(4)
	v_mfma_f32_32x32x16_bf16 v[0:15], v[158:161], v[174:177], v[0:15]
	v_mfma_f32_32x32x16_bf16 v[0:15], v[162:165], v[222:225], v[0:15]
	s_waitcnt lgkmcnt(0)
	v_mfma_f32_32x32x16_bf16 v[0:15], v[166:169], v[226:229], v[0:15]
	s_cmp_le_i32 s92, s91
	v_mfma_f32_32x32x16_bf16 v[0:15], v[170:173], v[230:233], v[0:15]
	s_cbranch_scc1 .LBB0_539
	v_subrev_u32_e32 v158, 64, v216
	v_cmp_gt_i32_e64 s[62:63], 26, v158
	v_cmp_gt_i32_e64 s[64:65], 27, v158
	v_cmp_gt_i32_e64 s[60:61], 25, v158
	s_and_b64 s[62:63], s[64:65], s[62:63]
	v_cmp_gt_i32_e64 s[58:59], 24, v158
	s_and_b64 s[60:61], s[62:63], s[60:61]
	v_cmp_gt_i32_e64 s[56:57], 19, v158
	s_and_b64 s[58:59], s[60:61], s[58:59]
	v_cmp_gt_i32_e64 s[54:55], 18, v158
	s_and_b64 s[56:57], s[58:59], s[56:57]
	v_cmp_gt_i32_e64 s[52:53], 17, v158
	s_and_b64 s[54:55], s[56:57], s[54:55]
	v_cmp_gt_i32_e64 s[50:51], 16, v158
	s_and_b64 s[52:53], s[54:55], s[52:53]
	v_cmp_gt_i32_e64 s[48:49], 11, v158
	s_and_b64 s[50:51], s[52:53], s[50:51]
	v_cmp_gt_i32_e64 s[46:47], 10, v158
	s_and_b64 s[48:49], s[50:51], s[48:49]
	v_cmp_gt_i32_e64 s[44:45], 9, v158
	s_and_b64 s[46:47], s[48:49], s[46:47]
	v_cmp_gt_i32_e64 s[42:43], 8, v158
	s_and_b64 s[44:45], s[46:47], s[44:45]
	v_cmp_gt_i32_e64 s[40:41], 3, v158
	s_and_b64 s[42:43], s[44:45], s[42:43]
	v_cmp_gt_i32_e64 s[38:39], 2, v158
	s_and_b64 s[40:41], s[42:43], s[40:41]
	v_cmp_gt_i32_e64 s[36:37], 1, v158
	s_and_b64 s[38:39], s[40:41], s[38:39]
	v_cmp_gt_i32_e64 s[34:35], 0, v158
	s_and_b64 s[36:37], s[38:39], s[36:37]
	s_and_b64 s[34:35], s[36:37], s[34:35]
	v_cmp_gt_i32_e64 s[28:29], 58, v158
	v_cndmask_b32_e64 v80, v80, v130, s[34:35]
	v_cmp_gt_i32_e64 s[34:35], 59, v158
	v_cmp_gt_i32_e64 s[26:27], 57, v158
	s_and_b64 s[28:29], s[34:35], s[28:29]
	v_cmp_gt_i32_e64 s[24:25], 56, v158
	s_and_b64 s[26:27], s[28:29], s[26:27]
	v_cmp_gt_i32_e64 s[22:23], 51, v158
	s_and_b64 s[24:25], s[26:27], s[24:25]
	v_cmp_gt_i32_e64 s[20:21], 50, v158
	s_and_b64 s[22:23], s[24:25], s[22:23]
	v_cmp_gt_i32_e64 s[18:19], 49, v158
	s_and_b64 s[20:21], s[22:23], s[20:21]
	v_cmp_gt_i32_e64 s[16:17], 48, v158
	s_and_b64 s[18:19], s[20:21], s[18:19]
	v_cmp_gt_i32_e64 s[14:15], 43, v158
	s_and_b64 s[16:17], s[18:19], s[16:17]
	v_cmp_gt_i32_e64 s[12:13], 42, v158
	s_and_b64 s[14:15], s[16:17], s[14:15]
	v_cmp_gt_i32_e64 s[10:11], 41, v158
	s_and_b64 s[12:13], s[14:15], s[12:13]
	v_cmp_gt_i32_e64 s[8:9], 40, v158
	s_and_b64 s[10:11], s[12:13], s[10:11]
	v_cmp_gt_i32_e64 s[6:7], 35, v158
	s_and_b64 s[8:9], s[10:11], s[8:9]
	v_cmp_gt_i32_e64 s[4:5], 34, v158
	s_and_b64 s[6:7], s[8:9], s[6:7]
	v_cmp_gt_i32_e64 s[2:3], 33, v158
	s_and_b64 s[4:5], s[6:7], s[4:5]
	v_cmp_gt_i32_e32 vcc, 32, v158
	s_and_b64 s[2:3], s[4:5], s[2:3]
	s_and_b64 vcc, s[2:3], vcc
	v_cndmask_b32_e64 v95, v95, v130, s[64:65]
	v_cndmask_b32_e64 v94, v94, v130, s[62:63]
	v_cndmask_b32_e64 v93, v93, v130, s[60:61]
	v_cndmask_b32_e64 v92, v92, v130, s[58:59]
	v_cndmask_b32_e64 v91, v91, v130, s[56:57]
	v_cndmask_b32_e64 v90, v90, v130, s[54:55]
	v_cndmask_b32_e64 v89, v89, v130, s[52:53]
	v_cndmask_b32_e64 v88, v88, v130, s[50:51]
	v_cndmask_b32_e64 v87, v87, v130, s[48:49]
	v_cndmask_b32_e64 v86, v86, v130, s[46:47]
	v_cndmask_b32_e64 v85, v85, v130, s[44:45]
	v_cndmask_b32_e64 v84, v84, v130, s[42:43]
	v_cndmask_b32_e64 v83, v83, v130, s[40:41]
	v_cndmask_b32_e64 v82, v82, v130, s[38:39]
	v_cndmask_b32_e64 v81, v81, v130, s[36:37]
	v_cndmask_b32_e64 v79, v79, v130, s[34:35]
	v_cndmask_b32_e64 v78, v78, v130, s[28:29]
	v_cndmask_b32_e64 v77, v77, v130, s[26:27]
	v_cndmask_b32_e64 v76, v76, v130, s[24:25]
	v_cndmask_b32_e64 v75, v75, v130, s[22:23]
	v_cndmask_b32_e64 v74, v74, v130, s[20:21]
	v_cndmask_b32_e64 v73, v73, v130, s[18:19]
	v_cndmask_b32_e64 v72, v72, v130, s[16:17]
	v_cndmask_b32_e64 v71, v71, v130, s[14:15]
	v_cndmask_b32_e64 v70, v70, v130, s[12:13]
	v_cndmask_b32_e64 v69, v69, v130, s[10:11]
	v_cndmask_b32_e64 v68, v68, v130, s[8:9]
	v_cndmask_b32_e64 v67, v67, v130, s[6:7]
	v_cndmask_b32_e64 v66, v66, v130, s[4:5]
	v_cndmask_b32_e64 v65, v65, v130, s[2:3]
	v_cndmask_b32_e32 v64, v64, v130, vcc

; #define SBAR() __builtin_amdgcn_sched_barrier(0)
; #define PV_RD(d0, kh, X) do { constexpr int b_ = v_rd_off(d0, 2 * (kh), 0); TRRD(X##l0, b_); TRRD(X##h0, b_ + 2048); TRRD(X##l1, b_ + 4096); TRRD(X##h1, b_ + 6144); } while (0)
; #define PV_MM(d0, X, PA, PB) do { \
;         o[d0] = __builtin_amdgcn_mfma_f32_32x32x16_bf16(PA, (bf16x8){X##l0[0], X##l0[1], X##l0[2], X##l0[3], X##h0[0], X##h0[1], X##h0[2], X##h0[3]}, o[d0], 0, 0, 0);   \
;         o[d0] = __builtin_amdgcn_mfma_f32_32x32x16_bf16(PB, (bf16x8){X##l1[0], X##l1[1], X##l1[2], X##l1[3], X##h1[0], X##h1[1], X##h1[2], X##h1[3]}, o[d0], 0, 0, 0); } while (0)
; #define PV_W4() do { asm volatile("s_waitcnt lgkmcnt(4)" ::: "memory"); SBAR(); } while (0)
; #define PV_W0() do { asm volatile("s_waitcnt lgkmcnt(0)" ::: "memory"); SBAR(); } while (0)
; __device__ __forceinline__ void finishSM(f32x16& p0, f32x16& p1, float alpha, float& l_reg, bf16x8& pa0, bf16x8& pa1, bf16x8& pa2, bf16x8& pa3) {
; #pragma unroll
;     for (int r = 0; r < 16; ++r) p1[r] = __builtin_amdgcn_exp2f(p1[r]);
;     float ps = 0;
; #pragma unroll
;     for (int r = 0; r < 16; ++r) ps += p0[r];
; #pragma unroll
;     for (int r = 0; r < 16; ++r) ps += p1[r];
;     { auto rr = __builtin_amdgcn_permlane32_swap(__float_as_uint(ps), __float_as_uint(ps), false, false);
;       ps = __uint_as_float(rr[0]) + __uint_as_float(rr[1]); }
;     l_reg = l_reg * alpha + ps;
;     ...
;     PK4(p0, 0, pa0); PK4(p0, 8, pa1); PK4(p1, 0, pa2); PK4(p1, 8, pa3);
; __device__ __forceinline__ void pv_tile(f32x16* o, int vb0, bf16x8 pa0, bf16x8 pa1, bf16x8 pa2, bf16x8 pa3) {
;     ...
;     s16x4 al0, al1, ah0, ah1, bl0, bl1, bh0, bh1;
;     PV_RD(0, 0, a);
;     PV_RD(0, 1, b); PV_W4(); PV_MM(0, a, pa0, pa1); SBAR();
;     PV_RD(1, 0, a); PV_W4(); PV_MM(0, b, pa2, pa3); SBAR();
;     PV_RD(1, 1, b); PV_W4(); PV_MM(1, a, pa0, pa1); SBAR();
;     PV_RD(2, 0, a); PV_W4(); PV_MM(1, b, pa2, pa3); SBAR();
;     PV_RD(2, 1, b); PV_W4(); PV_MM(2, a, pa0, pa1); SBAR();
;     PV_RD(3, 0, a); PV_W4(); PV_MM(2, b, pa2, pa3); SBAR();
;     PV_RD(3, 1, b); PV_W4(); PV_MM(3, a, pa0, pa1); SBAR();
;     PV_W0(); PV_MM(3, b, pa2, pa3);
.LBB0_553:
	ds_read_b128 v[198:201], v253
	ds_read_b128 v[202:205], v253 offset:1024
	s_waitcnt lgkmcnt(0)
	v_add_f32_e32 v64, 0, v221
	v_add_f32_e32 v64, v236, v64
	v_add_f32_e32 v64, v233, v64
	v_add_f32_e32 v64, v235, v64
	v_add_f32_e32 v64, v231, v64
	v_add_f32_e32 v64, v234, v64
	v_add_f32_e32 v64, v230, v64
	v_add_f32_e32 v64, v232, v64
	v_add_f32_e32 v64, v227, v64
	v_add_f32_e32 v64, v229, v64
	v_add_f32_e32 v64, v225, v64
	v_add_f32_e32 v64, v228, v64
	v_exp_f32_e32 v74, v168
	v_add_f32_e32 v64, v223, v64
	v_exp_f32_e32 v75, v169
	v_add_f32_e32 v64, v226, v64
	v_exp_f32_e32 v76, v172
	v_add_f32_e32 v64, v222, v64
	v_exp_f32_e32 v77, v173
	v_add_f32_e32 v64, v224, v64
	v_exp_f32_e32 v78, v176
	v_add_f32_e32 v64, v74, v64
	v_exp_f32_e32 v79, v177
	v_add_f32_e32 v64, v75, v64
	v_exp_f32_e32 v80, v166
	v_add_f32_e32 v64, v76, v64
	v_exp_f32_e32 v81, v167
	v_add_f32_e32 v64, v77, v64
	v_exp_f32_e32 v82, v170
	v_add_f32_e32 v64, v78, v64
	v_exp_f32_e32 v83, v171
	v_add_f32_e32 v64, v79, v64
	v_exp_f32_e32 v84, v174
	v_add_f32_e32 v64, v80, v64
	v_exp_f32_e32 v85, v175
	v_add_f32_e32 v64, v81, v64
	v_exp_f32_e32 v86, v178
	v_add_f32_e32 v64, v82, v64
	v_exp_f32_e32 v87, v179
	v_add_f32_e32 v64, v83, v64
	v_readlane_b32 s7, v247, 12
	v_readlane_b32 s2, v247, 13
	v_exp_f32_e32 v88, v164
	v_add_f32_e32 v64, v84, v64
	s_or_b32 s2, s7, s2
	v_exp_f32_e32 v89, v165
	v_add_f32_e32 v64, v85, v64
	s_ashr_i32 s3, s2, 31
	v_readlane_b32 s4, v248, 63
	v_add_f32_e32 v64, v86, v64
	s_lshl_b64 s[2:3], s[2:3], 11
	v_readlane_b32 s5, v247, 0
	v_add_f32_e32 v64, v87, v64
	s_or_b64 s[2:3], s[2:3], s[4:5]
	v_add_f32_e32 v64, v88, v64
	s_lshl_b64 s[68:69], s[2:3], 1
	v_readlane_b32 s93, v247, 10
	v_add_f32_e32 v64, v89, v64
	s_add_u32 s2, s93, s68
	v_readlane_b32 s3, v248, 37
	v_mov_b32_e32 v65, v64
	s_addc_u32 s3, s3, s69
	s_nop 0
	v_permlane32_swap_b32_e32 v64, v65
	v_cvt_pk_bf16_f32 v66, v221, v236
	v_cvt_pk_bf16_f32 v67, v233, v235
	v_cvt_pk_bf16_f32 v68, v231, v234
	v_cvt_pk_bf16_f32 v69, v230, v232
	v_cvt_pk_bf16_f32 v70, v227, v229
	v_cvt_pk_bf16_f32 v71, v225, v228
	v_cvt_pk_bf16_f32 v72, v223, v226
	v_cvt_pk_bf16_f32 v73, v222, v224
	v_cvt_pk_bf16_f32 v74, v74, v75
	v_cvt_pk_bf16_f32 v75, v76, v77
	v_cvt_pk_bf16_f32 v76, v78, v79
	v_cvt_pk_bf16_f32 v77, v80, v81
	v_cvt_pk_bf16_f32 v78, v82, v83
	v_cvt_pk_bf16_f32 v79, v84, v85
	v_cvt_pk_bf16_f32 v80, v86, v87
	v_cvt_pk_bf16_f32 v81, v88, v89
	s_nop 0
	v_permlane32_swap_b32_e32 v66, v68
	v_permlane32_swap_b32_e32 v67, v69
	v_permlane32_swap_b32_e32 v70, v72
	v_permlane32_swap_b32_e32 v71, v73
	v_permlane32_swap_b32_e32 v74, v76
	v_permlane32_swap_b32_e32 v75, v77
	v_permlane32_swap_b32_e32 v78, v80
	v_permlane32_swap_b32_e32 v79, v81
	v_add_u32_e32 v98, s76, v192
	ds_read_b64_tr_b16 v[82:83], v98 offset:0
	ds_read_b64_tr_b16 v[84:85], v98 offset:0x800
	ds_read_b64_tr_b16 v[86:87], v98 offset:0x1000
	ds_read_b64_tr_b16 v[88:89], v98 offset:0x1800
	ds_read_b64_tr_b16 v[90:91], v98 offset:0x2000
	ds_read_b64_tr_b16 v[92:93], v98 offset:0x2800
	ds_read_b64_tr_b16 v[94:95], v98 offset:0x3000
	ds_read_b64_tr_b16 v[96:97], v98 offset:0x3800
	s_waitcnt lgkmcnt(4)
	s_nop 0
	v_mfma_f32_32x32x16_bf16 v[48:63], v[66:69], v[82:85], v[48:63]
	v_mfma_f32_32x32x16_bf16 v[48:63], v[70:73], v[86:89], v[48:63]
	ds_read_b64_tr_b16 v[82:83], v98 offset:0x200
	ds_read_b64_tr_b16 v[84:85], v98 offset:0xa00
	ds_read_b64_tr_b16 v[86:87], v98 offset:0x1200
	ds_read_b64_tr_b16 v[88:89], v98 offset:0x1a00
	s_waitcnt lgkmcnt(4)
	v_mfma_f32_32x32x16_bf16 v[48:63], v[74:77], v[90:93], v[48:63]
	v_mfma_f32_32x32x16_bf16 v[48:63], v[78:81], v[94:97], v[48:63]
	ds_read_b64_tr_b16 v[90:91], v98 offset:0x2200
	ds_read_b64_tr_b16 v[92:93], v98 offset:0x2a00
	ds_read_b64_tr_b16 v[94:95], v98 offset:0x3200
	ds_read_b64_tr_b16 v[96:97], v98 offset:0x3a00
	s_waitcnt lgkmcnt(4)
	v_mfma_f32_32x32x16_bf16 v[32:47], v[66:69], v[82:85], v[32:47]
	v_mfma_f32_32x32x16_bf16 v[32:47], v[70:73], v[86:89], v[32:47]
	ds_read_b64_tr_b16 v[82:83], v98 offset:0x400
	ds_read_b64_tr_b16 v[84:85], v98 offset:0xc00
	ds_read_b64_tr_b16 v[86:87], v98 offset:0x1400
	ds_read_b64_tr_b16 v[88:89], v98 offset:0x1c00
	s_waitcnt lgkmcnt(4)
	v_mfma_f32_32x32x16_bf16 v[32:47], v[74:77], v[90:93], v[32:47]
	v_mfma_f32_32x32x16_bf16 v[32:47], v[78:81], v[94:97], v[32:47]
	ds_read_b64_tr_b16 v[90:91], v98 offset:0x2400
	ds_read_b64_tr_b16 v[92:93], v98 offset:0x2c00
	ds_read_b64_tr_b16 v[94:95], v98 offset:0x3400
	ds_read_b64_tr_b16 v[96:97], v98 offset:0x3c00
	s_waitcnt lgkmcnt(4)
	v_mfma_f32_32x32x16_bf16 v[16:31], v[66:69], v[82:85], v[16:31]
	v_mfma_f32_32x32x16_bf16 v[16:31], v[70:73], v[86:89], v[16:31]
	ds_read_b64_tr_b16 v[82:83], v98 offset:0x600
	ds_read_b64_tr_b16 v[84:85], v98 offset:0xe00
	ds_read_b64_tr_b16 v[86:87], v98 offset:0x1600
	ds_read_b64_tr_b16 v[88:89], v98 offset:0x1e00
	s_waitcnt lgkmcnt(4)
	v_mfma_f32_32x32x16_bf16 v[16:31], v[74:77], v[90:93], v[16:31]
	v_mfma_f32_32x32x16_bf16 v[16:31], v[78:81], v[94:97], v[16:31]
	ds_read_b64_tr_b16 v[90:91], v98 offset:0x2600
	ds_read_b64_tr_b16 v[92:93], v98 offset:0x2e00
	ds_read_b64_tr_b16 v[94:95], v98 offset:0x3600
	ds_read_b64_tr_b16 v[96:97], v98 offset:0x3e00
	s_waitcnt lgkmcnt(4)
	v_mfma_f32_32x32x16_bf16 v[0:15], v[66:69], v[82:85], v[0:15]
	v_mfma_f32_32x32x16_bf16 v[0:15], v[70:73], v[86:89], v[0:15]
	s_waitcnt lgkmcnt(0)
	v_mfma_f32_32x32x16_bf16 v[0:15], v[74:77], v[90:93], v[0:15]
	v_mfma_f32_32x32x16_bf16 v[0:15], v[78:81], v[94:97], v[0:15]
	v_lshl_add_u64 v[66:67], s[2:3], 0, v[132:133]
	v_mov_b32_e32 v147, v129
	s_waitcnt vmcnt(0) lgkmcnt(0)
	s_barrier
; #define LAS __attribute__((address_space(3)))
; __device__ __forceinline__ unsigned cvt_pk_bf16(float lo, float hi) { unsigned r; asm volatile("v_cvt_pk_bf16_f32 %0, %1, %2" : "=v"(r) : "v"(lo), "v"(hi)); return r; }
; __device__ __forceinline__ float bf_lo(unsigned w) { return __uint_as_float(w << 16); }
; #define SBAR() __builtin_amdgcn_sched_barrier(0)
; __device__ __forceinline__ void fox_block(const BlockRef& cur, const BlockRef& nxt, char* lds, Seam& S, const int tid) {
;     ...
;     { const bf16_t* Kh = nxt.K; const bf16_t* Vh = nxt.V;
; #pragma unroll
;       for (int d0 = 0; d0 < 8; ++d0) S.qr[d0] = load8(nxt.Q + (size_t)(wid * QBLK + r32) * LD + d0 * 16 + hi * 8);
;       SBAR(); DMA_K(0, 0); DMA_K(1, SLOT); DMA_V(0, 0); SBAR(); }
;     if (hi == 0) li_l[r32] = l_reg; asm volatile("s_waitcnt lgkmcnt(0)" ::: "memory");
;     float rli[16];
; #pragma unroll
;     for (int r = 0; r < 16; ++r) rli[r] = __builtin_amdgcn_rcpf(li_l[crow(r, hi)]);
;     typedef __attribute__((address_space(1))) bf16_t gbf16; typedef __attribute__((address_space(1))) u32x4 gu32x4;
;     LAS float* stg = (LAS float*)(lds3 + SLOT + wid * 4096);
;     const int er = lane >> 2, eq = lane & 3;
;     gbf16* obase = (gbf16*)(cur.O + (size_t)(wid * QBLK + er) * LD + 8 * eq); const gbf16* zbase = (const gbf16*)(cur.Z + (size_t)(wid * QBLK + er) * LD + 8 * eq);
; #pragma unroll
;     for (int d0 = 0; d0 < 4; ++d0) {
; #pragma unroll
;         for (int r = 0; r < 16; ++r) stg[crow(r, hi) * 32 + r32] = o[d0][r] * rli[r];
;         asm volatile("s_waitcnt lgkmcnt(0)" ::: "memory");
;         gbf16* op = obase; const gbf16* zp = zbase;
; #pragma unroll
;         for (int i = 0; i < 2; ++i) {
;             asm volatile("" : "+v"(op), "+v"(zp));
;             const f32x4 v0 = *(const LAS f32x4*)(stg + (er + 16 * i) * 32 + 8 * eq), v1 = *(const LAS f32x4*)(stg + (er + 16 * i) * 32 + 8 * eq + 4);
;             const u32x4 z = __builtin_nontemporal_load((const gu32x4*)(zp + d0 * 32));
;             u32x4 w; w.x = cvt_pk_bf16(v0.x * bf_lo(z.x), v0.y * bf_hi(z.x)); w.y = cvt_pk_bf16(v0.z * bf_lo(z.y), v0.w * bf_hi(z.y));
;             w.z = cvt_pk_bf16(v1.x * bf_lo(z.z), v1.y * bf_hi(z.z)); w.w = cvt_pk_bf16(v1.z * bf_lo(z.w), v1.w * bf_hi(z.w));
;             *(gu32x4*)(op + d0 * 32) = w;
;             op += 16 * LD; zp += 16 * LD; }
;         asm volatile("s_waitcnt lgkmcnt(0)" ::: "memory"); }
	v_lshl_add_u64 v[66:67], v[66:67], 0, v[146:147]
	global_load_dwordx4 v[96:99], v[66:67], off
	global_load_dwordx4 v[100:103], v[66:67], off offset:32
	global_load_dwordx4 v[104:107], v[66:67], off offset:64
	global_load_dwordx4 v[108:111], v[66:67], off offset:96
	global_load_dwordx4 v[112:115], v[66:67], off offset:128
	global_load_dwordx4 v[116:119], v[66:67], off offset:160
	global_load_dwordx4 v[120:123], v[66:67], off offset:192
	global_load_dwordx4 v[124:127], v[66:67], off offset:224
	v_readlane_b32 s2, v247, 15
	s_mov_b32 m0, s2
	v_readlane_b32 s2, v247, 16
	global_load_lds_dwordx4 v[144:145], off
	s_mov_b32 m0, s2
	v_readlane_b32 s2, v247, 17
	global_load_lds_dwordx4 v[142:143], off
	s_mov_b32 m0, s2
	v_readlane_b32 s2, v247, 18
	global_load_lds_dwordx4 v[136:137], off
	s_mov_b32 m0, s2
	v_readlane_b32 s2, v247, 19
	global_load_lds_dwordx4 v[138:139], off
	s_mov_b32 m0, s70
	s_nop 0
	global_load_lds_dwordx4 v[140:141], off
	s_mov_b32 m0, s2
	s_nop 0
	global_load_lds_dwordx4 v[134:135], off
	s_and_saveexec_b64 s[2:3], s[0:1]
	v_add_f32_e32 v64, v64, v65
	v_fmac_f32_e32 v64, v215, v158
	ds_write_b32 v214, v64
	s_or_b64 exec, exec, s[2:3]
	s_waitcnt lgkmcnt(0)
	ds_read_b128 v[64:67], v131
	ds_read_b128 v[68:71], v131 offset:32
	v_readlane_b32 s2, v248, 42
	s_add_u32 s2, s2, s78
	v_readlane_b32 s3, v248, 43
	s_waitcnt lgkmcnt(0)
	v_rcp_f32_e32 v72, v64
	v_rcp_f32_e32 v73, v65
	v_rcp_f32_e32 v74, v66
	v_rcp_f32_e32 v75, v67
	v_rcp_f32_e32 v76, v68
	ds_read_b128 v[64:67], v131 offset:64
	v_rcp_f32_e32 v77, v69
	v_rcp_f32_e32 v78, v70
	v_rcp_f32_e32 v79, v71
	ds_read_b128 v[68:71], v131 offset:96
	s_addc_u32 s3, s3, s79
	v_readlane_b32 s4, v248, 54
	s_add_u32 s4, s4, s78
	v_readlane_b32 s5, v248, 56
	v_readlane_b32 s6, v247, 14
	s_addc_u32 s5, s5, s79
	s_lshl_b32 s6, s6, 12
	s_waitcnt lgkmcnt(0)
	v_rcp_f32_e32 v84, v68
	s_add_i32 s6, s6, 0
	v_lshlrev_b32_e32 v68, 3, v155
	v_lshlrev_b32_e32 v133, 2, v199
	v_lshlrev_b32_e32 v170, 9, v213
	v_and_b32_e32 v132, 24, v68
	v_add3_u32 v68, s6, v133, v170
	v_rcp_f32_e32 v80, v64
	v_rcp_f32_e32 v81, v65
	v_mul_f32_e32 v48, v48, v72
	v_mul_f32_e32 v49, v49, v73
	v_add_u32_e32 v86, 0x4000, v68
	v_rcp_f32_e32 v82, v66
	v_rcp_f32_e32 v83, v67
	ds_write2_b32 v86, v48, v49 offset1:32
	v_mul_f32_e32 v48, v50, v74
	v_mul_f32_e32 v49, v51, v75
	v_rcp_f32_e32 v85, v69
	ds_write2_b32 v86, v48, v49 offset0:64 offset1:96
	v_mul_f32_e32 v48, v52, v76
	v_mul_f32_e32 v49, v53, v77
	v_add_u32_e32 v87, 0x4400, v68
	v_rcp_f32_e32 v70, v70
	v_rcp_f32_e32 v71, v71
	v_or_b32_e32 v64, s77, v191
	ds_write2_b32 v87, v48, v49 offset1:32
	v_mul_f32_e32 v48, v54, v78
	v_mul_f32_e32 v49, v55, v79
	v_ashrrev_i32_e32 v65, 31, v64
	ds_write2_b32 v87, v48, v49 offset0:64 offset1:96
	v_mul_f32_e32 v48, v56, v80
	v_mul_f32_e32 v49, v57, v81
	v_add_u32_e32 v88, 0x4800, v68
	v_lshlrev_b64 v[66:67], 12, v[64:65]
	ds_write2_b32 v88, v48, v49 offset1:32
	v_mul_f32_e32 v48, v58, v82
	v_mul_f32_e32 v49, v59, v83
	v_lshl_add_u64 v[64:65], s[4:5], 0, v[66:67]
	v_lshlrev_b32_e32 v128, 1, v132
	v_lshl_add_u64 v[66:67], s[2:3], 0, v[66:67]
	ds_write2_b32 v88, v48, v49 offset0:64 offset1:96
	v_mul_f32_e32 v48, v60, v84
	v_mul_f32_e32 v49, v61, v85
	v_add_u32_e32 v89, 0x4c00, v68
	v_lshl_add_u64 v[64:65], v[64:65], 0, v[128:129]
	v_lshl_add_u64 v[66:67], v[66:67], 0, v[128:129]
	ds_write2_b32 v89, v48, v49 offset1:32
	v_mul_f32_e32 v48, v62, v70
	v_mul_f32_e32 v49, v63, v71
	ds_write2_b32 v89, v48, v49 offset0:64 offset1:96
	v_mov_b64_e32 v[62:63], v[64:65]
	v_mov_b64_e32 v[68:69], v[66:67]
	s_waitcnt lgkmcnt(0)
	global_load_dwordx4 v[50:53], v[68:69], off nt
	v_add_co_u32_e32 v250, vcc, 0x10000, v68
	s_nop 1
	v_addc_co_u32_e32 v251, vcc, 0, v69, vcc
	global_load_dwordx4 v[222:225], v[250:251], off nt
	global_load_dwordx4 v[226:229], v[68:69], off offset:64 nt
	global_load_dwordx4 v[230:233], v[250:251], off offset:64 nt
	global_load_dwordx4 v[234:237], v[68:69], off offset:128 nt
	global_load_dwordx4 v[238:241], v[250:251], off offset:128 nt
	global_load_dwordx4 v[242:245], v[68:69], off offset:192 nt
	v_lshlrev_b32_e32 v145, 7, v191
	v_lshlrev_b32_e32 v48, 2, v132
	v_add3_u32 v48, s6, v48, v145
	ds_read_b128 v[54:57], v48 offset:16384
	ds_read_b128 v[58:61], v48 offset:16400
	s_mov_b64 s[2:3], 0x10000
	v_mul_f32_e32 v40, v40, v80
	v_mul_f32_e32 v41, v41, v81
	v_mul_f32_e32 v42, v42, v82
	v_mul_f32_e32 v43, v43, v83
	v_mul_f32_e32 v44, v44, v84
	v_mul_f32_e32 v45, v45, v85
	v_mul_f32_e32 v46, v46, v70
	v_mul_f32_e32 v47, v47, v71
	v_mul_f32_e32 v24, v24, v80
	v_mul_f32_e32 v25, v25, v81
	v_mul_f32_e32 v26, v26, v82
	v_mul_f32_e32 v27, v27, v83
	v_mul_f32_e32 v28, v28, v84
	v_mul_f32_e32 v29, v29, v85
	v_mul_f32_e32 v30, v30, v70
	v_mul_f32_e32 v31, v31, v71
	v_mul_f32_e32 v8, v8, v80
	v_mul_f32_e32 v9, v9, v81
	v_mul_f32_e32 v10, v10, v82
	v_mul_f32_e32 v11, v11, v83
	v_mul_f32_e32 v12, v12, v84
	v_mul_f32_e32 v13, v13, v85
	v_mul_f32_e32 v14, v14, v70
	v_mul_f32_e32 v15, v15, v71
	s_movk_i32 s6, 0x60
	s_or_b32 s4, s7, 64
	s_mov_b32 s87, 4
	s_lshr_b32 s89, s4, 6
	s_waitcnt vmcnt(6)
	v_lshlrev_b32_e32 v49, 16, v50
	v_and_b32_e32 v50, 0xffff0000, v50
	v_lshlrev_b32_e32 v90, 16, v51
	v_and_b32_e32 v51, 0xffff0000, v51
	v_lshlrev_b32_e32 v91, 16, v52
	v_and_b32_e32 v52, 0xffff0000, v52
	s_waitcnt lgkmcnt(1)
	v_mul_f32_e32 v50, v55, v50
	v_mul_f32_e32 v51, v57, v51
	v_lshlrev_b32_e32 v92, 16, v53
	v_and_b32_e32 v53, 0xffff0000, v53
	v_mul_f32_e32 v49, v54, v49
	v_mul_f32_e32 v54, v56, v90
	s_waitcnt lgkmcnt(0)
; #define LAS __attribute__((address_space(3)))
; __device__ __forceinline__ unsigned cvt_pk_bf16(float lo, float hi) { unsigned r; asm volatile("v_cvt_pk_bf16_f32 %0, %1, %2" : "=v"(r) : "v"(lo), "v"(hi)); return r; }
; __device__ __forceinline__ float bf_lo(unsigned w) { return __uint_as_float(w << 16); }
; __device__ __forceinline__ float bf_hi(unsigned w) { return __uint_as_float(w & 0xffff0000u); }
; __device__ __forceinline__ int crow(int r, int hi) { return (r & 3) + 8 * (r >> 2) + 4 * hi; }
; __device__ __forceinline__ void fox_block(const BlockRef& cur, const BlockRef& nxt, char* lds, Seam& S, const int tid) {
;     ...
;     for (int d0 = 0; d0 < 4; ++d0) {
; #pragma unroll
;         for (int r = 0; r < 16; ++r) stg[crow(r, hi) * 32 + r32] = o[d0][r] * rli[r];
;         asm volatile("s_waitcnt lgkmcnt(0)" ::: "memory");
;         gbf16* op = obase; const gbf16* zp = zbase;
; #pragma unroll
;         for (int i = 0; i < 2; ++i) {
;             asm volatile("" : "+v"(op), "+v"(zp));
;             const f32x4 v0 = *(const LAS f32x4*)(stg + (er + 16 * i) * 32 + 8 * eq), v1 = *(const LAS f32x4*)(stg + (er + 16 * i) * 32 + 8 * eq + 4);
;             const u32x4 z = __builtin_nontemporal_load((const gu32x4*)(zp + d0 * 32));
;             u32x4 w; w.x = cvt_pk_bf16(v0.x * bf_lo(z.x), v0.y * bf_hi(z.x)); w.y = cvt_pk_bf16(v0.z * bf_lo(z.y), v0.w * bf_hi(z.y));
;             w.z = cvt_pk_bf16(v1.x * bf_lo(z.z), v1.y * bf_hi(z.z)); w.w = cvt_pk_bf16(v1.z * bf_lo(z.w), v1.w * bf_hi(z.w));
;             *(gu32x4*)(op + d0 * 32) = w;
;             op += 16 * LD; zp += 16 * LD; }
;         asm volatile("s_waitcnt lgkmcnt(0)" ::: "memory"); }
	v_mul_f32_e32 v55, v58, v91
	v_mul_f32_e32 v52, v59, v52
	v_cvt_pk_bf16_f32 v50, v49, v50
	v_cvt_pk_bf16_f32 v51, v54, v51
	v_mul_f32_e32 v56, v60, v92
	v_cvt_pk_bf16_f32 v52, v55, v52
	v_mul_f32_e32 v49, v61, v53
	v_cvt_pk_bf16_f32 v53, v56, v49
	global_store_dwordx4 v[62:63], v[50:53], off
	v_lshl_add_u64 v[54:55], v[62:63], 0, s[2:3]
	v_mul_f32_e32 v49, v32, v72
	v_lshl_add_u64 v[50:51], v[68:69], 0, s[2:3]
	v_mul_f32_e32 v60, v33, v73
	v_mul_f32_e32 v61, v34, v74
	v_mul_f32_e32 v62, v35, v75
	v_mul_f32_e32 v63, v36, v76
	v_mul_f32_e32 v68, v37, v77
	v_mul_f32_e32 v69, v38, v78
	v_mul_f32_e32 v90, v39, v79
	ds_read_b128 v[32:35], v48 offset:18432
	ds_read_b128 v[36:39], v48 offset:18448
	v_mov_b64_e32 v[56:57], v[66:67]
	v_mov_b64_e32 v[58:59], v[64:65]
	s_waitcnt vmcnt(6)
	v_mov_b32_e32 v50, v222
	v_mov_b32_e32 v51, v223
	v_mov_b32_e32 v52, v224
	v_mov_b32_e32 v53, v225
	v_lshlrev_b32_e32 v91, 16, v50
	v_and_b32_e32 v50, 0xffff0000, v50
	v_lshlrev_b32_e32 v92, 16, v51
	v_and_b32_e32 v51, 0xffff0000, v51
	v_lshlrev_b32_e32 v93, 16, v52
	v_and_b32_e32 v52, 0xffff0000, v52
	v_lshlrev_b32_e32 v94, 16, v53
	v_and_b32_e32 v53, 0xffff0000, v53
	s_waitcnt lgkmcnt(1)
	v_mul_f32_e32 v32, v32, v91
	v_mul_f32_e32 v33, v33, v50
	v_mul_f32_e32 v34, v34, v92
	v_mul_f32_e32 v35, v35, v51
	s_waitcnt lgkmcnt(0)
	v_mul_f32_e32 v36, v36, v93
	v_mul_f32_e32 v37, v37, v52
	v_mul_f32_e32 v38, v38, v94
	v_mul_f32_e32 v39, v39, v53
	v_cvt_pk_bf16_f32 v32, v32, v33
	v_cvt_pk_bf16_f32 v33, v34, v35
	v_cvt_pk_bf16_f32 v34, v36, v37
	v_cvt_pk_bf16_f32 v35, v38, v39
	global_store_dwordx4 v[54:55], v[32:35], off
	s_waitcnt lgkmcnt(0)
	ds_write2_b32 v86, v49, v60 offset1:32
	ds_write2_b32 v86, v61, v62 offset0:64 offset1:96
	ds_write2_b32 v87, v63, v68 offset1:32
	ds_write2_b32 v87, v69, v90 offset0:64 offset1:96
	ds_write2_b32 v88, v40, v41 offset1:32
	ds_write2_b32 v88, v42, v43 offset0:64 offset1:96
	ds_write2_b32 v89, v44, v45 offset1:32
	ds_write2_b32 v89, v46, v47 offset0:64 offset1:96
	s_waitcnt lgkmcnt(0)
	ds_read_b128 v[36:39], v48 offset:16384
	ds_read_b128 v[40:43], v48 offset:16400
	v_lshl_add_u64 v[44:45], v[58:59], 0, s[2:3]
	v_lshl_add_u64 v[46:47], v[56:57], 0, s[2:3]
	s_waitcnt vmcnt(6)
	v_mov_b32_e32 v32, v226
	v_mov_b32_e32 v33, v227
	v_mov_b32_e32 v34, v228
	v_mov_b32_e32 v35, v229
	v_lshlrev_b32_e32 v49, 16, v32
	v_and_b32_e32 v32, 0xffff0000, v32
	v_lshlrev_b32_e32 v50, 16, v33
	v_and_b32_e32 v33, 0xffff0000, v33
	v_lshlrev_b32_e32 v51, 16, v34
	v_and_b32_e32 v34, 0xffff0000, v34
	v_lshlrev_b32_e32 v52, 16, v35
	v_and_b32_e32 v35, 0xffff0000, v35
	s_waitcnt lgkmcnt(1)
	v_mul_f32_e32 v32, v37, v32
	v_mul_f32_e32 v33, v39, v33
	s_waitcnt lgkmcnt(0)
	v_mul_f32_e32 v34, v41, v34
	v_mul_f32_e32 v35, v43, v35
	v_mul_f32_e32 v36, v36, v49
	v_mul_f32_e32 v37, v38, v50
	v_mul_f32_e32 v38, v40, v51
	v_mul_f32_e32 v39, v42, v52
	v_cvt_pk_bf16_f32 v32, v36, v32
	v_cvt_pk_bf16_f32 v33, v37, v33
	v_cvt_pk_bf16_f32 v34, v38, v34
	v_cvt_pk_bf16_f32 v35, v39, v35
	global_store_dwordx4 v[58:59], v[32:35], off offset:64
	v_mul_f32_e32 v40, v16, v72
	v_mul_f32_e32 v41, v17, v73
	v_mul_f32_e32 v42, v18, v74
	v_mul_f32_e32 v43, v19, v75
	v_mul_f32_e32 v46, v20, v76
	v_mul_f32_e32 v47, v21, v77
	v_mul_f32_e32 v49, v22, v78
	v_mul_f32_e32 v50, v23, v79
	ds_read_b128 v[16:19], v48 offset:18432
	ds_read_b128 v[20:23], v48 offset:18448
	v_mov_b64_e32 v[36:37], v[66:67]
	v_mov_b64_e32 v[38:39], v[64:65]
	s_waitcnt vmcnt(6)
	v_mov_b32_e32 v32, v230
	v_mov_b32_e32 v33, v231
	v_mov_b32_e32 v34, v232
	v_mov_b32_e32 v35, v233
	v_lshlrev_b32_e32 v51, 16, v32
	v_and_b32_e32 v32, 0xffff0000, v32
	v_lshlrev_b32_e32 v52, 16, v33
	v_and_b32_e32 v33, 0xffff0000, v33
	v_lshlrev_b32_e32 v53, 16, v34
	v_and_b32_e32 v34, 0xffff0000, v34
	v_lshlrev_b32_e32 v54, 16, v35
	v_and_b32_e32 v35, 0xffff0000, v35
	s_waitcnt lgkmcnt(1)
	v_mul_f32_e32 v16, v16, v51
	v_mul_f32_e32 v17, v17, v32
	v_mul_f32_e32 v18, v18, v52
	v_mul_f32_e32 v19, v19, v33
	s_waitcnt lgkmcnt(0)
	v_mul_f32_e32 v20, v20, v53
	v_mul_f32_e32 v21, v21, v34
	v_mul_f32_e32 v22, v22, v54
	v_mul_f32_e32 v23, v23, v35
	v_cvt_pk_bf16_f32 v16, v16, v17
	v_cvt_pk_bf16_f32 v17, v18, v19
	v_cvt_pk_bf16_f32 v18, v20, v21
	v_cvt_pk_bf16_f32 v19, v22, v23
	global_store_dwordx4 v[44:45], v[16:19], off offset:64
	s_waitcnt lgkmcnt(0)
	ds_write2_b32 v86, v40, v41 offset1:32
	ds_write2_b32 v86, v42, v43 offset0:64 offset1:96
	ds_write2_b32 v87, v46, v47 offset1:32
	ds_write2_b32 v87, v49, v50 offset0:64 offset1:96
	ds_write2_b32 v88, v24, v25 offset1:32
	ds_write2_b32 v88, v26, v27 offset0:64 offset1:96
	ds_write2_b32 v89, v28, v29 offset1:32
	ds_write2_b32 v89, v30, v31 offset0:64 offset1:96
	s_waitcnt lgkmcnt(0)
	ds_read_b128 v[20:23], v48 offset:16384
	ds_read_b128 v[24:27], v48 offset:16400
	v_lshl_add_u64 v[28:29], v[38:39], 0, s[2:3]
	v_lshl_add_u64 v[30:31], v[36:37], 0, s[2:3]
	s_waitcnt vmcnt(6)
	v_mov_b32_e32 v16, v234
	v_mov_b32_e32 v17, v235
	v_mov_b32_e32 v18, v236
	v_mov_b32_e32 v19, v237
	v_lshlrev_b32_e32 v32, 16, v16
	v_and_b32_e32 v16, 0xffff0000, v16
	v_lshlrev_b32_e32 v33, 16, v17
	v_and_b32_e32 v17, 0xffff0000, v17
	v_lshlrev_b32_e32 v34, 16, v18
	v_and_b32_e32 v18, 0xffff0000, v18
	v_lshlrev_b32_e32 v35, 16, v19
	v_and_b32_e32 v19, 0xffff0000, v19
	s_waitcnt lgkmcnt(1)
	v_mul_f32_e32 v16, v21, v16
	v_mul_f32_e32 v17, v23, v17
	s_waitcnt lgkmcnt(0)
; #define LAS __attribute__((address_space(3)))
; __device__ __forceinline__ unsigned cvt_pk_bf16(float lo, float hi) { unsigned r; asm volatile("v_cvt_pk_bf16_f32 %0, %1, %2" : "=v"(r) : "v"(lo), "v"(hi)); return r; }
; __device__ __forceinline__ float bf_lo(unsigned w) { return __uint_as_float(w << 16); }
; __device__ __forceinline__ float bf_hi(unsigned w) { return __uint_as_float(w & 0xffff0000u); }
; __device__ __forceinline__ int v_rd_base(int lane) { return ((lane & 3) << 3) | (((lane >> 2) & 3) << 6) | (((lane >> 4) & 1) << 5) | (((lane >> 5) & 1) << 8); }
; __device__ __forceinline__ void fox_block(const BlockRef& cur, const BlockRef& nxt, char* lds, Seam& S, const int tid) {
;     const int wid = __builtin_amdgcn_readfirstlane(tid >> 6), lane = tid & 63, r32 = lane & 31, hi = lane >> 5;
;     const int NT = cur.P0 / KVBLK + 4;
;     const int qlo = cur.P0 + wid * QBLK, qm = qlo + r32 - 4 * hi;
;     char* V_lds = lds; char* K_lds = lds + OFF_K; LAS unsigned char* lds3 = (LAS unsigned char*)lds;
;     float* ws = (float*)(lds + OFF_WS) + wid * 64; float* li_l = ws, * al_l = ws + 32;
;     const LAS float* ctab = (const LAS float*)(LAS char*)(lds + OFF_C);
;     float m_reg = -1e30f, l_reg = 0; f32x16 o[4] = {};
;     const DmaOff dof = dma_offsets(wid, lane);
;     const int vb0 = (int)(uintptr_t)V_lds + v_rd_base(lane);
;     ...
;     for (int d0 = 0; d0 < 4; ++d0) {
; #pragma unroll
;         for (int r = 0; r < 16; ++r) stg[crow(r, hi) * 32 + r32] = o[d0][r] * rli[r];
;         asm volatile("s_waitcnt lgkmcnt(0)" ::: "memory");
;         gbf16* op = obase; const gbf16* zp = zbase;
; #pragma unroll
;         for (int i = 0; i < 2; ++i) {
;             asm volatile("" : "+v"(op), "+v"(zp));
;             const f32x4 v0 = *(const LAS f32x4*)(stg + (er + 16 * i) * 32 + 8 * eq), v1 = *(const LAS f32x4*)(stg + (er + 16 * i) * 32 + 8 * eq + 4);
;             const u32x4 z = __builtin_nontemporal_load((const gu32x4*)(zp + d0 * 32));
;             u32x4 w; w.x = cvt_pk_bf16(v0.x * bf_lo(z.x), v0.y * bf_hi(z.x)); w.y = cvt_pk_bf16(v0.z * bf_lo(z.y), v0.w * bf_hi(z.y));
;             w.z = cvt_pk_bf16(v1.x * bf_lo(z.z), v1.y * bf_hi(z.z)); w.w = cvt_pk_bf16(v1.z * bf_lo(z.w), v1.w * bf_hi(z.w));
;             *(gu32x4*)(op + d0 * 32) = w;
;             op += 16 * LD; zp += 16 * LD; }
;         asm volatile("s_waitcnt lgkmcnt(0)" ::: "memory"); }
;     WAITV_BAR(0);
	v_mul_f32_e32 v18, v25, v18
	v_mul_f32_e32 v19, v27, v19
	v_mul_f32_e32 v20, v20, v32
	v_mul_f32_e32 v21, v22, v33
	v_mul_f32_e32 v22, v24, v34
	v_mul_f32_e32 v23, v26, v35
	v_cvt_pk_bf16_f32 v16, v20, v16
	v_cvt_pk_bf16_f32 v17, v21, v17
	v_cvt_pk_bf16_f32 v18, v22, v18
	v_cvt_pk_bf16_f32 v19, v23, v19
	global_store_dwordx4 v[38:39], v[16:19], off offset:128
	v_mul_f32_e32 v20, v0, v72
	v_mul_f32_e32 v21, v1, v73
	v_mul_f32_e32 v22, v2, v74
	v_mul_f32_e32 v23, v3, v75
	v_mul_f32_e32 v24, v4, v76
	v_mul_f32_e32 v25, v5, v77
	v_mul_f32_e32 v26, v6, v78
	v_mul_f32_e32 v27, v7, v79
	ds_read_b128 v[0:3], v48 offset:18432
	ds_read_b128 v[4:7], v48 offset:18448
	s_waitcnt vmcnt(6)
	v_mov_b32_e32 v16, v238
	v_mov_b32_e32 v17, v239
	v_mov_b32_e32 v18, v240
	v_mov_b32_e32 v19, v241
	v_lshlrev_b32_e32 v30, 16, v16
	v_and_b32_e32 v16, 0xffff0000, v16
	v_lshlrev_b32_e32 v31, 16, v17
	v_and_b32_e32 v17, 0xffff0000, v17
	v_lshlrev_b32_e32 v32, 16, v18
	v_and_b32_e32 v18, 0xffff0000, v18
	v_lshlrev_b32_e32 v33, 16, v19
	v_and_b32_e32 v19, 0xffff0000, v19
	s_waitcnt lgkmcnt(1)
	v_mul_f32_e32 v0, v0, v30
	v_mul_f32_e32 v1, v1, v16
	v_mul_f32_e32 v2, v2, v31
	v_mul_f32_e32 v3, v3, v17
	s_waitcnt lgkmcnt(0)
	v_mul_f32_e32 v4, v4, v32
	v_mul_f32_e32 v5, v5, v18
	v_mul_f32_e32 v6, v6, v33
	v_mul_f32_e32 v7, v7, v19
	v_cvt_pk_bf16_f32 v0, v0, v1
	v_cvt_pk_bf16_f32 v1, v2, v3
	v_cvt_pk_bf16_f32 v2, v4, v5
	v_cvt_pk_bf16_f32 v3, v6, v7
	global_store_dwordx4 v[28:29], v[0:3], off offset:128
	s_waitcnt lgkmcnt(0)
	ds_write2_b32 v86, v20, v21 offset1:32
	ds_write2_b32 v86, v22, v23 offset0:64 offset1:96
	ds_write2_b32 v87, v24, v25 offset1:32
	ds_write2_b32 v87, v26, v27 offset0:64 offset1:96
	ds_write2_b32 v88, v8, v9 offset1:32
	ds_write2_b32 v88, v10, v11 offset0:64 offset1:96
	ds_write2_b32 v89, v12, v13 offset1:32
	ds_write2_b32 v89, v14, v15 offset0:64 offset1:96
	s_waitcnt lgkmcnt(0)
	ds_read_b128 v[4:7], v48 offset:16384
	ds_read_b128 v[8:11], v48 offset:16400
	v_lshl_add_u64 v[12:13], v[64:65], 0, s[2:3]
	v_lshl_add_u64 v[14:15], v[66:67], 0, s[2:3]
	v_readfirstlane_b32 s3, v155
	s_ashr_i32 s70, s3, 6
	s_lshl_b32 s5, s70, 7
	s_and_b32 s3, s3, 0x3fffffc0
	v_readlane_b32 s2, v248, 61
	s_lshl_b32 s3, s3, 2
	s_and_b32 s2, s2, 0x700
	s_lshl_b32 s71, s70, 5
	s_add_i32 s3, s3, 0
	s_add_i32 s3, s3, 0x18000
	s_waitcnt vmcnt(6)
	v_mov_b32_e32 v0, v242
	v_mov_b32_e32 v1, v243
	v_mov_b32_e32 v2, v244
	v_mov_b32_e32 v3, v245
	v_lshlrev_b32_e32 v16, 16, v0
	v_and_b32_e32 v0, 0xffff0000, v0
	v_lshlrev_b32_e32 v17, 16, v1
	v_and_b32_e32 v1, 0xffff0000, v1
	v_lshlrev_b32_e32 v18, 16, v2
	v_and_b32_e32 v2, 0xffff0000, v2
	v_lshlrev_b32_e32 v19, 16, v3
	v_and_b32_e32 v3, 0xffff0000, v3
	s_waitcnt lgkmcnt(1)
	v_mul_f32_e32 v0, v5, v0
	v_mul_f32_e32 v1, v7, v1
	s_waitcnt lgkmcnt(0)
	v_mul_f32_e32 v2, v9, v2
	v_mul_f32_e32 v3, v11, v3
	v_mul_f32_e32 v4, v4, v16
	v_mul_f32_e32 v5, v6, v17
	v_mul_f32_e32 v6, v8, v18
	v_mul_f32_e32 v7, v10, v19
	v_cvt_pk_bf16_f32 v0, v4, v0
	v_cvt_pk_bf16_f32 v1, v5, v1
	v_cvt_pk_bf16_f32 v2, v6, v2
	v_cvt_pk_bf16_f32 v3, v7, v3
	global_store_dwordx4 v[64:65], v[0:3], off offset:192
	global_load_dwordx4 v[0:3], v[14:15], off offset:192 nt
	v_or_b32_e32 v4, s5, v198
	s_ashr_i32 s5, s5, 4
	v_bitop3_b32 v36, s5, -13, v191 bitop3:0xc8
	s_lshr_b32 s5, s5, 1
	v_ashrrev_i32_e32 v5, 4, v4
	s_and_b32 s5, s5, 4
	v_or_b32_e32 v14, 64, v4
	v_bitop3_b32 v4, v5, v203, 15 bitop3:0x6c
	v_lshlrev_b32_e32 v5, 8, v5
	v_or3_b32 v6, v36, s5, v200
	v_lshl_or_b32 v128, v4, 4, v5
	v_lshlrev_b32_e32 v17, 8, v6
	ds_read_b128 v[4:7], v48 offset:18432
	ds_read_b128 v[8:11], v48 offset:18448
	v_ashrrev_i32_e32 v15, 4, v14
	v_bitop3_b32 v16, v15, v203, 15 bitop3:0x6c
	v_or_b32_e32 v134, v17, v204
	s_waitcnt vmcnt(0)
	v_lshlrev_b32_e32 v18, 16, v0
	v_and_b32_e32 v0, 0xffff0000, v0
	v_lshlrev_b32_e32 v19, 16, v1
	v_and_b32_e32 v1, 0xffff0000, v1
	v_lshlrev_b32_e32 v20, 16, v2
	v_and_b32_e32 v2, 0xffff0000, v2
	v_lshlrev_b32_e32 v21, 16, v3
	v_and_b32_e32 v3, 0xffff0000, v3
	s_waitcnt lgkmcnt(1)
	v_mul_f32_e32 v0, v5, v0
	v_mul_f32_e32 v1, v7, v1
	s_waitcnt lgkmcnt(0)
	v_mul_f32_e32 v2, v9, v2
	v_mul_f32_e32 v3, v11, v3
	v_mul_f32_e32 v4, v4, v18
	v_mul_f32_e32 v5, v6, v19
	v_mul_f32_e32 v6, v8, v20
	v_mul_f32_e32 v7, v10, v21
	v_cvt_pk_bf16_f32 v0, v4, v0
	v_cvt_pk_bf16_f32 v1, v5, v1
	v_cvt_pk_bf16_f32 v2, v6, v2
	v_cvt_pk_bf16_f32 v3, v7, v3
	global_store_dwordx4 v[12:13], v[0:3], off offset:192
	s_waitcnt lgkmcnt(0)
	s_waitcnt vmcnt(0) lgkmcnt(0)
	s_barrier
; #define LAS __attribute__((address_space(3)))
; #define SBAR() __builtin_amdgcn_sched_barrier(0)
; __device__ __forceinline__ int v_rd_base(int lane) { return ((lane & 3) << 3) | (((lane >> 2) & 3) << 6) | (((lane >> 4) & 1) << 5) | (((lane >> 5) & 1) << 8); }
; #define WAITV_BAR(N) asm volatile("s_waitcnt vmcnt(" #N ") lgkmcnt(0)\n\ts_barrier" ::: "memory")
; #define DMA_K(t, slot) do { _Pragma("unroll") for (int i_ = 0; i_ < 2; ++i_) __builtin_amdgcn_global_load_lds((const unsigned*)((const char*)Kh + (size_t)(t) * (KVBLK * D * 2) + dof.k[i_]), \
;         (LAS unsigned*)((LAS unsigned char*)lds3 + OFF_K + (slot) + (wid * 2 + i_) * 1024), 16, 0, 0); } while (0)
; #define DMA_V(t, slot) do { _Pragma("unroll") for (int i_ = 0; i_ < 2; ++i_) __builtin_amdgcn_global_load_lds((const unsigned*)((const char*)Vh + (size_t)(t) * (KVBLK * D * 2) + dof.v[i_]), \
;         (LAS unsigned*)((LAS unsigned char*)lds3 + (slot) + (wid * 2 + i_) * 1024), 16, 0, 0); } while (0)
; #define ROT() do { s_prev = s_cur; s_cur = s_next; s_next = s_nn; s_nn = (s_nn == (NSLOT - 1) * SLOT) ? 0 : s_nn + SLOT; } while (0)
; __device__ __forceinline__ void fox_block(const BlockRef& cur, const BlockRef& nxt, char* lds, Seam& S, const int tid) {
;     const int wid = __builtin_amdgcn_readfirstlane(tid >> 6), lane = tid & 63, r32 = lane & 31, hi = lane >> 5;
;     const int NT = cur.P0 / KVBLK + 4;
;     const int qlo = cur.P0 + wid * QBLK, qm = qlo + r32 - 4 * hi;
;     char* V_lds = lds; char* K_lds = lds + OFF_K; LAS unsigned char* lds3 = (LAS unsigned char*)lds;
;     float* ws = (float*)(lds + OFF_WS) + wid * 64; float* li_l = ws, * al_l = ws + 32;
;     const LAS float* ctab = (const LAS float*)(LAS char*)(lds + OFF_C);
;     float m_reg = -1e30f, l_reg = 0; f32x16 o[4] = {};
;     const DmaOff dof = dma_offsets(wid, lane);
;     const int vb0 = (int)(uintptr_t)V_lds + v_rd_base(lane);
;     const bf16_t* Kh = cur.K; const bf16_t* Vh = cur.V;
;     ...
;     f32x16 pA0, pA1, pB0, pB1; float mnA, mnB, alA, alB; bf16x8 pa0, pa1, pa2, pa3;
;     int s_prev = 0, s_cur = 0, s_next = SLOT, s_nn = 2 * SLOT;
;     SBAR(); DMA_K(2, s_nn); DMA_V(1, s_next); SBAR();
;     qkt(pA0, pA1, K_lds + s_cur, r32, hi, S.qr, CTP(0));
;     mask_meta(pA0, pA1); partialSM(pA0, pA1, m_reg, mnA, alA);
;     SBAR(); WAITV_BAR(4);
;     ROT();
	s_nop 1
	v_lshlrev_b32_e32 v0, 8, v15
	v_lshl_or_b32 v138, v16, 4, v0
	v_and_or_b32 v0, v14, s6, v202
	v_lshl_or_b32 v136, v0, 1, v17
	s_lshl_b32 s6, s70, 11
	s_add_i32 s86, s6, 0
	s_add_i32 m0, s86, 0x14000
	v_readlane_b32 s6, v247, 24
	global_load_lds_dwordx4 v128, s[66:67]
	s_add_i32 m0, s86, 0x14400
	v_readlane_b32 s7, v247, 25
	global_load_lds_dwordx4 v138, s[66:67]
	s_add_i32 m0, s86, 0x4000
	v_mov_b32_e32 v139, v129
	s_add_i32 s88, s71, s4
	s_nop 0
	global_load_lds_dwordx4 v134, s[6:7]
	s_add_i32 m0, s86, 0x4400
	s_movk_i32 s73, 0x4000
	global_load_lds_dwordx4 v136, s[6:7]
	v_mov_b32_e32 v135, v129
	v_mov_b32_e32 v137, v129
	s_add_i32 s89, s89, 4
	ds_read_b128 v[16:19], v209 offset:57344
	ds_read_b128 v[0:3], v205 offset:128
	ds_read_b128 v[4:7], v205 offset:160
	ds_read_b128 v[8:11], v205 offset:192
	ds_read_b128 v[12:15], v205 offset:224
	v_xor_b32_e32 v249, 0x80, v209
	v_xor_b32_e32 v250, 0x80, v208
	v_xor_b32_e32 v251, 0x80, v207
	v_xor_b32_e32 v252, 0x80, v206
	ds_read_b128 v[20:23], v249 offset:57344
	s_mov_b32 s4, 0xff800000
	s_waitcnt lgkmcnt(0)
	v_mfma_f32_32x32x16_bf16 v[0:15], v[16:19], v[96:99], v[0:15]
	ds_read_b128 v[16:19], v208 offset:57344
	ds_read_b128 v[24:27], v250 offset:57344
	s_waitcnt lgkmcnt(0)
	v_mfma_f32_32x32x16_bf16 v[0:15], v[16:19], v[100:103], v[0:15]
	ds_read_b128 v[16:19], v207 offset:57344
	ds_read_b128 v[28:31], v251 offset:57344
	s_waitcnt lgkmcnt(0)
	v_mfma_f32_32x32x16_bf16 v[0:15], v[16:19], v[104:107], v[0:15]
	ds_read_b128 v[16:19], v206 offset:57344
	ds_read_b128 v[32:35], v252 offset:57344
	s_waitcnt lgkmcnt(0)
	v_mfma_f32_32x32x16_bf16 v[0:15], v[16:19], v[108:111], v[0:15]
	v_mfma_f32_32x32x16_bf16 v[0:15], v[20:23], v[112:115], v[0:15]
	v_mfma_f32_32x32x16_bf16 v[0:15], v[24:27], v[116:119], v[0:15]
	v_mfma_f32_32x32x16_bf16 v[0:15], v[28:31], v[120:123], v[0:15]
	v_mfma_f32_32x32x16_bf16 v[0:15], v[32:35], v[124:127], v[0:15]
	s_nop 11
	v_max3_f32 v0, v8, s4, v9
	v_max3_f32 v0, v0, v10, v11
	v_max3_f32 v0, v0, v12, v13
	v_max3_f32 v0, v0, v14, v15
	v_mov_b32_e32 v1, v0
	s_nop 1
	v_permlane32_swap_b32_e32 v0, v1
	v_max_f32_e32 v1, v1, v1
	v_max_f32_e32 v0, v0, v0
	v_max_f32_e32 v0, v0, v1
	v_add_f32_e32 v1, 0x7149f2ca, v0
	v_cmp_ge_f32_e32 vcc, s33, v1
	s_cmp_eq_u64 vcc, exec
	v_max_f32_e32 v2, 0xf149f2ca, v0
	s_cselect_b64 vcc, -1, 0
	v_cndmask_b32_e32 v144, v2, v189, vcc
	v_mov_b32_e32 v0, v9
	v_mov_b32_e32 v1, v10
	v_pk_add_f32 v[66:67], v[0:1], v[144:145] op_sel_hi:[1,0] neg_lo:[0,1] neg_hi:[0,1]
	v_mov_b32_e32 v0, v11
	v_mov_b32_e32 v1, v12
	v_pk_add_f32 v[68:69], v[0:1], v[144:145] op_sel_hi:[1,0] neg_lo:[0,1] neg_hi:[0,1]
	v_sub_f32_e32 v1, 0xf149f2ca, v2
	v_mov_b32_e32 v131, v8
	v_mov_b32_e32 v0, v13
	v_exp_f32_e32 v2, v1
	v_mov_b32_e32 v1, v14
	s_add_i32 s2, s2, s71
	v_pk_add_f32 v[64:65], v[130:131], v[144:145] op_sel_hi:[1,0] neg_lo:[0,1] neg_hi:[0,1]
	v_pk_add_f32 v[70:71], v[0:1], v[144:145] op_sel_hi:[1,0] neg_lo:[0,1] neg_hi:[0,1]
	v_or_b32_e32 v0, s2, v199
	v_exp_f32_e32 v178, v64
	v_sub_u32_e32 v173, v0, v201
	v_add_u32_e32 v0, v36, v200
	v_add_lshl_u32 v0, v0, s5, 8
	s_waitcnt vmcnt(4) lgkmcnt(0)
	s_barrier
	v_or_b32_e32 v1, v0, v211
	v_mov_b32_e32 v48, v129
	v_mov_b32_e32 v49, v129
	v_sub_f32_e32 v155, v15, v144
	v_cndmask_b32_e64 v174, v2, 1.0, vcc
	v_add_u32_e32 v140, v1, v210
	v_or3_b32 v142, v0, v212, v210
	v_mov_b32_e32 v50, v129
	v_mov_b32_e32 v51, v129
	v_mov_b32_e32 v52, v129
	v_mov_b32_e32 v53, v129
	v_mov_b32_e32 v54, v129
	v_mov_b32_e32 v55, v129
	v_mov_b32_e32 v56, v129
	v_mov_b32_e32 v57, v129
	v_mov_b32_e32 v58, v129
	v_mov_b32_e32 v59, v129
	v_mov_b32_e32 v60, v129
	v_mov_b32_e32 v61, v129
	v_mov_b32_e32 v62, v129
	v_mov_b32_e32 v63, v129
	v_mov_b64_e32 v[32:33], v[48:49]
	v_mov_b64_e32 v[16:17], v[48:49]
	v_mov_b64_e32 v[0:1], v[48:49]
	v_add_u32_e32 v171, s3, v133
	v_lshl_add_u32 v131, v201, 2, s3
	v_mov_b32_e32 v141, v129
	v_mov_b32_e32 v143, v129
	s_mov_b32 s2, 0
	v_mov_b32_e32 v172, 0
	s_mov_b32 s90, 0x8000
	s_movk_i32 s91, 0xbf
	v_mov_b64_e32 v[34:35], v[50:51]
	v_mov_b64_e32 v[36:37], v[52:53]
	v_mov_b64_e32 v[38:39], v[54:55]
	v_mov_b64_e32 v[40:41], v[56:57]
	v_mov_b64_e32 v[42:43], v[58:59]
	v_mov_b64_e32 v[44:45], v[60:61]
	v_mov_b64_e32 v[46:47], v[62:63]
	v_mov_b64_e32 v[18:19], v[50:51]
	v_mov_b64_e32 v[20:21], v[52:53]
	v_mov_b64_e32 v[22:23], v[54:55]
	v_mov_b64_e32 v[24:25], v[56:57]
	v_mov_b64_e32 v[26:27], v[58:59]
	v_mov_b64_e32 v[28:29], v[60:61]
	v_mov_b64_e32 v[30:31], v[62:63]
	v_mov_b64_e32 v[2:3], v[50:51]
	v_mov_b64_e32 v[4:5], v[52:53]
	v_mov_b64_e32 v[6:7], v[54:55]
	v_mov_b64_e32 v[8:9], v[56:57]
	v_mov_b64_e32 v[10:11], v[58:59]
	v_mov_b64_e32 v[12:13], v[60:61]
	v_mov_b64_e32 v[14:15], v[62:63]
	s_mov_b32 s72, 0
	v_mov_b32_e32 v211, v178
	v_mov_b32_e32 v208, v178
	v_mov_b32_e32 v210, v178
	v_mov_b32_e32 v206, v178
	v_mov_b32_e32 v209, v178
	v_mov_b32_e32 v205, v178
	v_mov_b32_e32 v207, v178
	v_mov_b32_e32 v202, v178
	v_mov_b32_e32 v204, v178
	v_mov_b32_e32 v200, v178
	v_mov_b32_e32 v203, v178
	v_mov_b32_e32 v198, v178
	v_mov_b32_e32 v201, v178
	v_mov_b32_e32 v179, v178
	v_mov_b32_e32 v199, v178
	v_mov_b32_e32 v158, v64
	v_mov_b32_e32 v159, v64
	v_mov_b32_e32 v162, v64
	v_mov_b32_e32 v163, v64
	v_mov_b32_e32 v166, v64
	v_mov_b32_e32 v167, v64
	v_mov_b32_e32 v156, v64
	v_mov_b32_e32 v157, v64
	v_mov_b32_e32 v160, v65
	v_mov_b32_e32 v161, v66
	v_mov_b32_e32 v164, v67
	v_mov_b32_e32 v165, v68
	v_mov_b32_e32 v168, v69
	v_mov_b32_e32 v169, v70
	v_mov_b32_e32 v154, v71
	v_readlane_b32 s96, v247, 9
	v_readlane_b32 s97, v247, 8

; #define LAS __attribute__((address_space(3)))
; __device__ __forceinline__ void finishSM(f32x16& p0, f32x16& p1, float alpha, float& l_reg, bf16x8& pa0, bf16x8& pa1, bf16x8& pa2, bf16x8& pa3) {
; #pragma unroll
;     for (int r = 0; r < 16; ++r) p1[r] = __builtin_amdgcn_exp2f(p1[r]);
;     float ps = 0;
; #pragma unroll
;     for (int r = 0; r < 16; ++r) ps += p0[r];
; #pragma unroll
;     for (int r = 0; r < 16; ++r) ps += p1[r];
;     { auto rr = __builtin_amdgcn_permlane32_swap(__float_as_uint(ps), __float_as_uint(ps), false, false);
;       ps = __uint_as_float(rr[0]) + __uint_as_float(rr[1]); }
;     l_reg = l_reg * alpha + ps;
;     ...
;     PK4(p0, 0, pa0); PK4(p0, 8, pa1); PK4(p1, 0, pa2); PK4(p1, 8, pa3);
; __device__ __forceinline__ void qkt(f32x16& p0, f32x16& p1, const char* Kslot, int r32, int hi, const bf16x8* qr, const LAS f32x4* cp) {
; #pragma unroll
;     for (int g = 0; g < 4; ++g) { const f32x4 c0 = cp[2 * g], c1 = cp[8 + 2 * g];
; #pragma unroll
;         for (int j = 0; j < 4; ++j) { p0[4 * g + j] = c0[j]; p1[4 * g + j] = c1[j]; } }
;     const char* kb[4];
; #pragma unroll
;     for (int dd = 0; dd < 4; ++dd) kb[dd] = Kslot + KSWZ(r32, (dd * 16 + hi * 8) * 2);
; #pragma unroll
;     for (int d0 = 0; d0 < 8; ++d0) { const char* a = kb[d0 & 3] + (d0 >> 2) * 128;
;         bf16x8 b0 = *reinterpret_cast<const bf16x8*>(a);
;         bf16x8 b1 = *reinterpret_cast<const bf16x8*>(a + 32 * 256);
;         p0 = __builtin_amdgcn_mfma_f32_32x32x16_bf16(b0, qr[d0], p0, 0, 0, 0);
;         p1 = __builtin_amdgcn_mfma_f32_32x32x16_bf16(b1, qr[d0], p1, 0, 0, 0); }
.LBB0_558:
	s_add_i32 s3, s86, s90
	v_lshl_add_u64 v[150:151], s[82:83], 0, v[140:141]
	v_lshl_add_u64 v[64:65], v[150:151], 0, s[84:85]
	s_mov_b32 m0, s3
	v_lshl_add_u64 v[152:153], s[82:83], 0, v[142:143]
	global_load_lds_dwordx4 v[64:65], off
	v_lshl_add_u64 v[64:65], v[152:153], 0, s[84:85]
	s_add_i32 m0, s3, 0x400
	s_nop 0
	global_load_lds_dwordx4 v[64:65], off
	s_add_i32 s3, s73, 0
	v_add_u32_e32 v175, s3, v193
	v_add_u32_e32 v176, s3, v194
	v_add_u32_e32 v177, s3, v195
	v_add_u32_e32 v220, s3, v196
	v_xor_b32_e32 v249, 0x80, v175
	v_xor_b32_e32 v250, 0x80, v176
	v_xor_b32_e32 v251, 0x80, v177
	v_xor_b32_e32 v252, 0x80, v220
	ds_read_b128 v[80:83], v197
	ds_read_b128 v[84:87], v197 offset:32
	ds_read_b128 v[64:67], v197 offset:128
	ds_read_b128 v[68:71], v197 offset:160
	ds_read_b128 v[88:91], v197 offset:64
	ds_read_b128 v[72:75], v197 offset:192
	ds_read_b128 v[92:95], v197 offset:96
	ds_read_b128 v[76:79], v197 offset:224
	ds_read_b128 v[212:215], v175 offset:49152
	ds_read_b128 v[216:219], v175 offset:57344
	ds_read_b128 v[222:225], v176 offset:49152
	ds_read_b128 v[226:229], v176 offset:57344
	ds_read_b128 v[230:233], v177 offset:49152
	ds_read_b128 v[234:237], v177 offset:57344
	s_waitcnt lgkmcnt(4)
	v_mfma_f32_32x32x16_bf16 v[80:95], v[212:215], v[96:99], v[80:95]
	v_exp_f32_e32 v163, v163
	v_exp_f32_e32 v166, v166
	v_exp_f32_e32 v167, v167
	v_exp_f32_e32 v168, v168
	v_exp_f32_e32 v169, v169
	v_exp_f32_e32 v221, v155
	v_mfma_f32_32x32x16_bf16 v[64:79], v[216:219], v[96:99], v[64:79]
	ds_read_b128 v[212:215], v220 offset:49152
	ds_read_b128 v[216:219], v220 offset:57344
	s_waitcnt lgkmcnt(4)
	v_mfma_f32_32x32x16_bf16 v[80:95], v[222:225], v[100:103], v[80:95]
	v_mfma_f32_32x32x16_bf16 v[64:79], v[226:229], v[100:103], v[64:79]
	ds_read_b128 v[222:225], v249 offset:49152
	ds_read_b128 v[226:229], v249 offset:57344
	s_waitcnt lgkmcnt(4)
	v_mfma_f32_32x32x16_bf16 v[80:95], v[230:233], v[104:107], v[80:95]
	v_mfma_f32_32x32x16_bf16 v[64:79], v[234:237], v[104:107], v[64:79]
	ds_read_b128 v[230:233], v250 offset:49152
	ds_read_b128 v[234:237], v250 offset:57344
	s_waitcnt lgkmcnt(4)
	v_mfma_f32_32x32x16_bf16 v[80:95], v[212:215], v[108:111], v[80:95]
	v_mfma_f32_32x32x16_bf16 v[64:79], v[216:219], v[108:111], v[64:79]
	ds_read_b128 v[212:215], v251 offset:49152
	ds_read_b128 v[216:219], v251 offset:57344
	s_waitcnt lgkmcnt(4)
	v_mfma_f32_32x32x16_bf16 v[80:95], v[222:225], v[112:115], v[80:95]
	v_mfma_f32_32x32x16_bf16 v[64:79], v[226:229], v[112:115], v[64:79]
	ds_read_b128 v[222:225], v252 offset:49152
	ds_read_b128 v[226:229], v252 offset:57344
	s_waitcnt lgkmcnt(4)
	v_mfma_f32_32x32x16_bf16 v[80:95], v[230:233], v[116:119], v[80:95]
	v_mfma_f32_32x32x16_bf16 v[64:79], v[234:237], v[116:119], v[64:79]
	v_exp_f32_e32 v177, v158
	s_waitcnt lgkmcnt(2)
	v_mfma_f32_32x32x16_bf16 v[80:95], v[212:215], v[120:123], v[80:95]
	v_mfma_f32_32x32x16_bf16 v[64:79], v[216:219], v[120:123], v[64:79]
	v_exp_f32_e32 v220, v154
	v_add_f32_e32 v154, 0, v178
	v_add_f32_e32 v154, v211, v154
	v_add_f32_e32 v154, v208, v154
	v_add_f32_e32 v154, v210, v154
	v_add_f32_e32 v154, v206, v154
	v_add_f32_e32 v154, v209, v154
	v_add_f32_e32 v154, v205, v154
	v_add_f32_e32 v154, v207, v154
	v_add_f32_e32 v154, v202, v154
	v_add_f32_e32 v154, v204, v154
	v_add_f32_e32 v154, v200, v154
	v_add_f32_e32 v154, v203, v154
	v_add_f32_e32 v154, v198, v154
	s_waitcnt lgkmcnt(0)
	v_mfma_f32_32x32x16_bf16 v[80:95], v[222:225], v[124:127], v[80:95]
	v_exp_f32_e32 v212, v159
	v_add_f32_e32 v154, v201, v154
	v_exp_f32_e32 v213, v162
	v_add_f32_e32 v154, v179, v154
	v_add_f32_e32 v154, v199, v154
	v_add_f32_e32 v154, v177, v154
	v_add_f32_e32 v154, v212, v154
	v_exp_f32_e32 v214, v156
	v_add_f32_e32 v154, v213, v154
	v_exp_f32_e32 v215, v157
	v_add_f32_e32 v154, v163, v154
	v_mfma_f32_32x32x16_bf16 v[64:79], v[226:229], v[124:127], v[64:79]
	v_exp_f32_e32 v216, v160
	v_add_f32_e32 v154, v166, v154
	v_exp_f32_e32 v217, v161
	v_add_f32_e32 v154, v167, v154
	v_exp_f32_e32 v218, v164
	v_add_f32_e32 v154, v214, v154
	v_exp_f32_e32 v219, v165
	v_add_f32_e32 v154, v215, v154
	v_add_f32_e32 v154, v216, v154
	v_add_f32_e32 v154, v217, v154
	v_add_f32_e32 v154, v218, v154
	v_add_f32_e32 v154, v219, v154
	v_add_f32_e32 v154, v168, v154
	v_add_f32_e32 v154, v169, v154
	v_add_f32_e32 v154, v220, v154
	v_add_f32_e32 v175, v221, v154
	v_mov_b32_e32 v176, v175
	s_nop 1
	v_permlane32_swap_b32_e32 v175, v176
	v_cvt_pk_bf16_f32 v154, v178, v211
	v_cvt_pk_bf16_f32 v155, v208, v210
	v_cvt_pk_bf16_f32 v156, v206, v209
	v_cvt_pk_bf16_f32 v157, v205, v207
	v_cvt_pk_bf16_f32 v158, v202, v204
	v_cvt_pk_bf16_f32 v159, v200, v203
	v_cvt_pk_bf16_f32 v160, v198, v201
	v_cvt_pk_bf16_f32 v161, v179, v199
	v_cvt_pk_bf16_f32 v162, v177, v212
	v_cvt_pk_bf16_f32 v163, v213, v163
	v_cvt_pk_bf16_f32 v164, v166, v167
	v_cvt_pk_bf16_f32 v165, v214, v215
	v_cvt_pk_bf16_f32 v166, v216, v217
	v_cvt_pk_bf16_f32 v167, v218, v219
	v_cvt_pk_bf16_f32 v168, v168, v169
	v_cvt_pk_bf16_f32 v169, v220, v221
	s_nop 0
	v_permlane32_swap_b32_e32 v154, v156
	v_permlane32_swap_b32_e32 v155, v157
	v_permlane32_swap_b32_e32 v158, v160
	v_permlane32_swap_b32_e32 v159, v161
	v_permlane32_swap_b32_e32 v162, v164
	v_permlane32_swap_b32_e32 v163, v165
	v_permlane32_swap_b32_e32 v166, v168
	v_permlane32_swap_b32_e32 v167, v169
	v_add_u32_e32 v177, s2, v192
	ds_read_b64_tr_b16 v[198:199], v177 offset:0
	ds_read_b64_tr_b16 v[200:201], v177 offset:0x800
	ds_read_b64_tr_b16 v[202:203], v177 offset:0x1000
	ds_read_b64_tr_b16 v[204:205], v177 offset:0x1800
	ds_read_b64_tr_b16 v[206:207], v177 offset:0x2000
	ds_read_b64_tr_b16 v[208:209], v177 offset:0x2800
	ds_read_b64_tr_b16 v[210:211], v177 offset:0x3000
	ds_read_b64_tr_b16 v[212:213], v177 offset:0x3800
	s_waitcnt lgkmcnt(4)
; #define SBAR() __builtin_amdgcn_sched_barrier(0)
; #define PV_RD(d0, kh, X) do { constexpr int b_ = v_rd_off(d0, 2 * (kh), 0); TRRD(X##l0, b_); TRRD(X##h0, b_ + 2048); TRRD(X##l1, b_ + 4096); TRRD(X##h1, b_ + 6144); } while (0)
; #define PV_MM(d0, X, PA, PB) do { \
;         o[d0] = __builtin_amdgcn_mfma_f32_32x32x16_bf16(PA, (bf16x8){X##l0[0], X##l0[1], X##l0[2], X##l0[3], X##h0[0], X##h0[1], X##h0[2], X##h0[3]}, o[d0], 0, 0, 0);   \
;         o[d0] = __builtin_amdgcn_mfma_f32_32x32x16_bf16(PB, (bf16x8){X##l1[0], X##l1[1], X##l1[2], X##l1[3], X##h1[0], X##h1[1], X##h1[2], X##h1[3]}, o[d0], 0, 0, 0); } while (0)
; #define PV_W4() do { asm volatile("s_waitcnt lgkmcnt(4)" ::: "memory"); SBAR(); } while (0)
; #define PV_W0() do { asm volatile("s_waitcnt lgkmcnt(0)" ::: "memory"); SBAR(); } while (0)
; __device__ __forceinline__ void mask_tile(f32x16& p0, f32x16& p1, int dq) {
;     const float NEG = -__builtin_inff();
; #pragma unroll
;     for (int r = 0; r < 16; ++r) { const int c = (r & 3) + 8 * (r >> 2); if (dq - c < 0) p0[r] = NEG; if (dq - c - 32 < 0) p1[r] = NEG; }
; }
; __device__ __forceinline__ void pv_tile(f32x16* o, int vb0, bf16x8 pa0, bf16x8 pa1, bf16x8 pa2, bf16x8 pa3) {
;     ...
;     s16x4 al0, al1, ah0, ah1, bl0, bl1, bh0, bh1;
;     PV_RD(0, 0, a);
;     PV_RD(0, 1, b); PV_W4(); PV_MM(0, a, pa0, pa1); SBAR();
;     PV_RD(1, 0, a); PV_W4(); PV_MM(0, b, pa2, pa3); SBAR();
;     PV_RD(1, 1, b); PV_W4(); PV_MM(1, a, pa0, pa1); SBAR();
;     PV_RD(2, 0, a); PV_W4(); PV_MM(1, b, pa2, pa3); SBAR();
;     PV_RD(2, 1, b); PV_W4(); PV_MM(2, a, pa0, pa1); SBAR();
;     PV_RD(3, 0, a); PV_W4(); PV_MM(2, b, pa2, pa3); SBAR();
;     PV_RD(3, 1, b); PV_W4(); PV_MM(3, a, pa0, pa1); SBAR();
;     PV_W0(); PV_MM(3, b, pa2, pa3);
	s_nop 0
	v_mfma_f32_32x32x16_bf16 v[48:63], v[154:157], v[198:201], v[48:63]
	v_mfma_f32_32x32x16_bf16 v[48:63], v[158:161], v[202:205], v[48:63]
	ds_read_b64_tr_b16 v[198:199], v177 offset:0x200
	ds_read_b64_tr_b16 v[200:201], v177 offset:0xa00
	ds_read_b64_tr_b16 v[202:203], v177 offset:0x1200
	ds_read_b64_tr_b16 v[204:205], v177 offset:0x1a00
	s_waitcnt lgkmcnt(4)
	v_mfma_f32_32x32x16_bf16 v[48:63], v[162:165], v[206:209], v[48:63]
	v_mfma_f32_32x32x16_bf16 v[48:63], v[166:169], v[210:213], v[48:63]
	ds_read_b64_tr_b16 v[206:207], v177 offset:0x2200
	ds_read_b64_tr_b16 v[208:209], v177 offset:0x2a00
	ds_read_b64_tr_b16 v[210:211], v177 offset:0x3200
	ds_read_b64_tr_b16 v[212:213], v177 offset:0x3a00
	s_waitcnt lgkmcnt(4)
	v_mfma_f32_32x32x16_bf16 v[32:47], v[154:157], v[198:201], v[32:47]
	v_mfma_f32_32x32x16_bf16 v[32:47], v[158:161], v[202:205], v[32:47]
	ds_read_b64_tr_b16 v[198:199], v177 offset:0x400
	ds_read_b64_tr_b16 v[200:201], v177 offset:0xc00
	ds_read_b64_tr_b16 v[202:203], v177 offset:0x1400
	ds_read_b64_tr_b16 v[204:205], v177 offset:0x1c00
	s_waitcnt lgkmcnt(4)
	v_mfma_f32_32x32x16_bf16 v[32:47], v[162:165], v[206:209], v[32:47]
	v_mfma_f32_32x32x16_bf16 v[32:47], v[166:169], v[210:213], v[32:47]
	ds_read_b64_tr_b16 v[206:207], v177 offset:0x2400
	ds_read_b64_tr_b16 v[208:209], v177 offset:0x2c00
	ds_read_b64_tr_b16 v[210:211], v177 offset:0x3400
	ds_read_b64_tr_b16 v[212:213], v177 offset:0x3c00
	s_waitcnt lgkmcnt(4)
	v_mfma_f32_32x32x16_bf16 v[16:31], v[154:157], v[198:201], v[16:31]
	v_mfma_f32_32x32x16_bf16 v[16:31], v[158:161], v[202:205], v[16:31]
	ds_read_b64_tr_b16 v[198:199], v177 offset:0x600
	ds_read_b64_tr_b16 v[200:201], v177 offset:0xe00
	ds_read_b64_tr_b16 v[202:203], v177 offset:0x1600
	ds_read_b64_tr_b16 v[204:205], v177 offset:0x1e00
	s_waitcnt lgkmcnt(4)
	v_mfma_f32_32x32x16_bf16 v[16:31], v[162:165], v[206:209], v[16:31]
	v_mfma_f32_32x32x16_bf16 v[16:31], v[166:169], v[210:213], v[16:31]
	ds_read_b64_tr_b16 v[206:207], v177 offset:0x2600
	ds_read_b64_tr_b16 v[208:209], v177 offset:0x2e00
	ds_read_b64_tr_b16 v[210:211], v177 offset:0x3600
	ds_read_b64_tr_b16 v[212:213], v177 offset:0x3e00
	s_waitcnt lgkmcnt(4)
	v_mfma_f32_32x32x16_bf16 v[0:15], v[154:157], v[198:201], v[0:15]
	v_mfma_f32_32x32x16_bf16 v[0:15], v[158:161], v[202:205], v[0:15]
	s_waitcnt lgkmcnt(0)
	v_mfma_f32_32x32x16_bf16 v[0:15], v[162:165], v[206:209], v[0:15]
	s_sub_i32 s2, s91, 64
	s_cmp_le_i32 s2, s88
	v_mfma_f32_32x32x16_bf16 v[0:15], v[166:169], v[210:213], v[0:15]
	s_cbranch_scc1 .LBB0_560
	v_cmp_gt_i32_e64 s[62:63], 26, v173
	v_cmp_gt_i32_e64 s[64:65], 27, v173
	v_cmp_gt_i32_e64 s[60:61], 25, v173
	s_and_b64 s[62:63], s[64:65], s[62:63]
	v_cmp_gt_i32_e64 s[58:59], 24, v173
	s_and_b64 s[60:61], s[62:63], s[60:61]
	v_cmp_gt_i32_e64 s[56:57], 19, v173
	s_and_b64 s[58:59], s[60:61], s[58:59]
	v_cmp_gt_i32_e64 s[54:55], 18, v173
	s_and_b64 s[56:57], s[58:59], s[56:57]
	v_cmp_gt_i32_e64 s[52:53], 17, v173
	s_and_b64 s[54:55], s[56:57], s[54:55]
	v_cmp_gt_i32_e64 s[50:51], 16, v173
	s_and_b64 s[52:53], s[54:55], s[52:53]
	v_cmp_gt_i32_e64 s[48:49], 11, v173
	s_and_b64 s[50:51], s[52:53], s[50:51]
	v_cmp_gt_i32_e64 s[46:47], 10, v173
	s_and_b64 s[48:49], s[50:51], s[48:49]
	v_cmp_gt_i32_e64 s[44:45], 9, v173
	s_and_b64 s[46:47], s[48:49], s[46:47]
	v_cmp_gt_i32_e64 s[42:43], 8, v173
	s_and_b64 s[44:45], s[46:47], s[44:45]
	v_cmp_gt_i32_e64 s[40:41], 3, v173
	s_and_b64 s[42:43], s[44:45], s[42:43]
	v_cmp_gt_i32_e64 s[38:39], 2, v173
	s_and_b64 s[40:41], s[42:43], s[40:41]
	v_cmp_gt_i32_e64 s[36:37], 1, v173
	s_and_b64 s[38:39], s[40:41], s[38:39]
	v_cmp_gt_i32_e64 s[34:35], 0, v173
	s_and_b64 s[36:37], s[38:39], s[36:37]
	s_and_b64 s[34:35], s[36:37], s[34:35]
	v_cmp_gt_i32_e64 s[28:29], 58, v173
	v_cndmask_b32_e64 v80, v80, v130, s[34:35]
	v_cmp_gt_i32_e64 s[34:35], 59, v173
	v_cmp_gt_i32_e64 s[26:27], 57, v173
	s_and_b64 s[28:29], s[34:35], s[28:29]
	v_cmp_gt_i32_e64 s[24:25], 56, v173
	s_and_b64 s[26:27], s[28:29], s[26:27]
	v_cmp_gt_i32_e64 s[22:23], 51, v173
	s_and_b64 s[24:25], s[26:27], s[24:25]
	v_cmp_gt_i32_e64 s[20:21], 50, v173
	s_and_b64 s[22:23], s[24:25], s[22:23]
	v_cmp_gt_i32_e64 s[18:19], 49, v173
	s_and_b64 s[20:21], s[22:23], s[20:21]
	v_cmp_gt_i32_e64 s[16:17], 48, v173
	s_and_b64 s[18:19], s[20:21], s[18:19]
	v_cmp_gt_i32_e64 s[14:15], 43, v173
	s_and_b64 s[16:17], s[18:19], s[16:17]
	v_cmp_gt_i32_e64 s[12:13], 42, v173
	s_and_b64 s[14:15], s[16:17], s[14:15]
	v_cmp_gt_i32_e64 s[10:11], 41, v173
	s_and_b64 s[12:13], s[14:15], s[12:13]
	v_cmp_gt_i32_e64 s[8:9], 40, v173
	s_and_b64 s[10:11], s[12:13], s[10:11]
	v_cmp_gt_i32_e64 s[6:7], 35, v173
	s_and_b64 s[8:9], s[10:11], s[8:9]
	v_cmp_gt_i32_e64 s[4:5], 34, v173
	s_and_b64 s[6:7], s[8:9], s[6:7]
	v_cmp_gt_i32_e64 s[2:3], 33, v173
	s_and_b64 s[4:5], s[6:7], s[4:5]
	v_cmp_gt_i32_e32 vcc, 32, v173
	s_and_b64 s[2:3], s[4:5], s[2:3]
	s_and_b64 vcc, s[2:3], vcc
	v_cndmask_b32_e64 v95, v95, v130, s[64:65]
	v_cndmask_b32_e64 v94, v94, v130, s[62:63]
	v_cndmask_b32_e64 v93, v93, v130, s[60:61]
	v_cndmask_b32_e64 v92, v92, v130, s[58:59]
	v_cndmask_b32_e64 v91, v91, v130, s[56:57]
	v_cndmask_b32_e64 v90, v90, v130, s[54:55]
	v_cndmask_b32_e64 v89, v89, v130, s[52:53]
	v_cndmask_b32_e64 v88, v88, v130, s[50:51]
	v_cndmask_b32_e64 v87, v87, v130, s[48:49]
	v_cndmask_b32_e64 v86, v86, v130, s[46:47]
	v_cndmask_b32_e64 v85, v85, v130, s[44:45]
	v_cndmask_b32_e64 v84, v84, v130, s[42:43]
	v_cndmask_b32_e64 v83, v83, v130, s[40:41]
	v_cndmask_b32_e64 v82, v82, v130, s[38:39]
	v_cndmask_b32_e64 v81, v81, v130, s[36:37]
	v_cndmask_b32_e64 v79, v79, v130, s[34:35]
	v_cndmask_b32_e64 v78, v78, v130, s[28:29]
	v_cndmask_b32_e64 v77, v77, v130, s[26:27]
	v_cndmask_b32_e64 v76, v76, v130, s[24:25]
	v_cndmask_b32_e64 v75, v75, v130, s[22:23]
	v_cndmask_b32_e64 v74, v74, v130, s[20:21]
	v_cndmask_b32_e64 v73, v73, v130, s[18:19]
	v_cndmask_b32_e64 v72, v72, v130, s[16:17]
	v_cndmask_b32_e64 v71, v71, v130, s[14:15]
	v_cndmask_b32_e64 v70, v70, v130, s[12:13]
	v_cndmask_b32_e64 v69, v69, v130, s[10:11]
	v_cndmask_b32_e64 v68, v68, v130, s[8:9]
	v_cndmask_b32_e64 v67, v67, v130, s[6:7]
	v_cndmask_b32_e64 v66, v66, v130, s[4:5]
	v_cndmask_b32_e64 v65, v65, v130, s[2:3]
	v_cndmask_b32_e32 v64, v64, v130, vcc

; #define LAS __attribute__((address_space(3)))
; __device__ __forceinline__ void partialSM(f32x16& p0, f32x16& p1, float& m_reg, float& mn, float& alpha) {
;     ...
; #pragma unroll
;     for (int r = 0; r < 16; ++r) p0[r] = p0[r] - mn;
; #pragma unroll
;     for (int r = 0; r < 16; ++r) p1[r] = p1[r] - mn;
; #pragma unroll
;     for (int r = 0; r < 16; ++r) p0[r] = __builtin_amdgcn_exp2f(p0[r]);
; __device__ __forceinline__ void finishSM(f32x16& p0, f32x16& p1, float alpha, float& l_reg, bf16x8& pa0, bf16x8& pa1, bf16x8& pa2, bf16x8& pa3) {
; #pragma unroll
;     for (int r = 0; r < 16; ++r) p1[r] = __builtin_amdgcn_exp2f(p1[r]);
;     float ps = 0;
; #pragma unroll
;     for (int r = 0; r < 16; ++r) ps += p0[r];
; #pragma unroll
;     for (int r = 0; r < 16; ++r) ps += p1[r];
;     { auto rr = __builtin_amdgcn_permlane32_swap(__float_as_uint(ps), __float_as_uint(ps), false, false);
;       ps = __uint_as_float(rr[0]) + __uint_as_float(rr[1]); }
;     l_reg = l_reg * alpha + ps;
;     ...
;     PK4(p0, 0, pa0); PK4(p0, 8, pa1); PK4(p1, 0, pa2); PK4(p1, 8, pa3);
; __device__ __forceinline__ void qkt(f32x16& p0, f32x16& p1, const char* Kslot, int r32, int hi, const bf16x8* qr, const LAS f32x4* cp) {
; #pragma unroll
;     for (int g = 0; g < 4; ++g) { const f32x4 c0 = cp[2 * g], c1 = cp[8 + 2 * g];
; #pragma unroll
;         for (int j = 0; j < 4; ++j) { p0[4 * g + j] = c0[j]; p1[4 * g + j] = c1[j]; } }
;     const char* kb[4];
; #pragma unroll
;     for (int dd = 0; dd < 4; ++dd) kb[dd] = Kslot + KSWZ(r32, (dd * 16 + hi * 8) * 2);
; #pragma unroll
;     for (int d0 = 0; d0 < 8; ++d0) { const char* a = kb[d0 & 3] + (d0 >> 2) * 128;
;         bf16x8 b0 = *reinterpret_cast<const bf16x8*>(a);
;         bf16x8 b1 = *reinterpret_cast<const bf16x8*>(a + 32 * 256);
;         p0 = __builtin_amdgcn_mfma_f32_32x32x16_bf16(b0, qr[d0], p0, 0, 0, 0);
;         p1 = __builtin_amdgcn_mfma_f32_32x32x16_bf16(b1, qr[d0], p1, 0, 0, 0); }
.LBB0_572:
	v_cndmask_b32_e64 v144, v154, v144, s[2:3]
	v_sub_f32_e32 v80, v80, v144
	v_sub_f32_e32 v81, v81, v144
	v_sub_f32_e32 v82, v82, v144
	v_sub_f32_e32 v83, v83, v144
	v_sub_f32_e32 v84, v84, v144
	v_sub_f32_e32 v85, v85, v144
	v_sub_f32_e32 v86, v86, v144
	v_sub_f32_e32 v87, v87, v144
	v_sub_f32_e32 v88, v88, v144
	v_sub_f32_e32 v89, v89, v144
	v_sub_f32_e32 v90, v90, v144
	v_sub_f32_e32 v91, v91, v144
	v_sub_f32_e32 v92, v92, v144
	v_sub_f32_e32 v93, v93, v144
	v_sub_f32_e32 v94, v94, v144
	v_sub_f32_e32 v95, v95, v144
	v_sub_f32_e32 v154, v64, v144
	v_sub_f32_e32 v155, v65, v144
	v_sub_f32_e32 v156, v66, v144
	v_sub_f32_e32 v157, v67, v144
	v_sub_f32_e32 v158, v68, v144
	v_sub_f32_e32 v159, v69, v144
	v_sub_f32_e32 v160, v70, v144
	v_sub_f32_e32 v161, v71, v144
	v_sub_f32_e32 v162, v72, v144
	v_sub_f32_e32 v163, v73, v144
	v_sub_f32_e32 v164, v74, v144
	v_sub_f32_e32 v165, v75, v144
	v_sub_f32_e32 v166, v76, v144
	v_exp_f32_e32 v167, v80
	v_exp_f32_e32 v168, v81
	v_exp_f32_e32 v169, v82
	v_exp_f32_e32 v178, v83
	v_exp_f32_e32 v179, v84
	v_exp_f32_e32 v198, v85
	v_exp_f32_e32 v199, v86
	v_exp_f32_e32 v200, v87
	v_exp_f32_e32 v201, v88
	v_exp_f32_e32 v202, v89
	v_exp_f32_e32 v203, v90
	v_exp_f32_e32 v204, v91
	v_exp_f32_e32 v205, v92
	v_exp_f32_e32 v206, v93
	v_exp_f32_e32 v207, v94
	v_exp_f32_e32 v208, v95
	v_sub_f32_e32 v209, v77, v144
	v_sub_f32_e32 v210, v78, v144
	v_sub_f32_e32 v211, v79, v144
	s_add_i32 s2, s90, 0
	v_add_u32_e32 v212, s2, v193
	v_add_u32_e32 v213, s2, v194
	v_add_u32_e32 v214, s2, v195
	v_add_u32_e32 v215, s2, v196
	v_xor_b32_e32 v249, 0x80, v212
	v_xor_b32_e32 v250, 0x80, v213
	v_xor_b32_e32 v251, 0x80, v214
	v_xor_b32_e32 v252, 0x80, v215
	ds_read_b128 v[80:83], v197 offset:256
	ds_read_b128 v[84:87], v197 offset:288
	ds_read_b128 v[64:67], v197 offset:384
	ds_read_b128 v[68:71], v197 offset:416
	ds_read_b128 v[88:91], v197 offset:320
	ds_read_b128 v[72:75], v197 offset:448
	ds_read_b128 v[92:95], v197 offset:352
	ds_read_b128 v[76:79], v197 offset:480
	ds_read_b128 v[146:149], v212 offset:49152
	ds_read_b128 v[150:153], v212 offset:57344
	ds_read_b128 v[222:225], v213 offset:49152
	ds_read_b128 v[226:229], v213 offset:57344
	ds_read_b128 v[230:233], v214 offset:49152
	ds_read_b128 v[234:237], v214 offset:57344
	s_waitcnt lgkmcnt(4)
	v_mfma_f32_32x32x16_bf16 v[80:95], v[146:149], v[96:99], v[80:95]
	v_exp_f32_e32 v157, v157
	v_exp_f32_e32 v158, v158
	v_exp_f32_e32 v159, v159
	v_exp_f32_e32 v160, v160
	v_exp_f32_e32 v161, v161
	v_exp_f32_e32 v162, v162
	v_mfma_f32_32x32x16_bf16 v[64:79], v[150:153], v[96:99], v[64:79]
	ds_read_b128 v[146:149], v215 offset:49152
	ds_read_b128 v[150:153], v215 offset:57344
	v_exp_f32_e32 v163, v163
	v_exp_f32_e32 v164, v164
	v_exp_f32_e32 v165, v165
	v_exp_f32_e32 v166, v166
	v_exp_f32_e32 v209, v209
	v_exp_f32_e32 v210, v210
	s_waitcnt lgkmcnt(4)
	v_mfma_f32_32x32x16_bf16 v[80:95], v[222:225], v[100:103], v[80:95]
	v_exp_f32_e32 v211, v211
	v_mfma_f32_32x32x16_bf16 v[64:79], v[226:229], v[100:103], v[64:79]
	ds_read_b128 v[222:225], v249 offset:49152
	ds_read_b128 v[226:229], v249 offset:57344
	s_waitcnt lgkmcnt(4)
	v_mfma_f32_32x32x16_bf16 v[80:95], v[230:233], v[104:107], v[80:95]
	v_mfma_f32_32x32x16_bf16 v[64:79], v[234:237], v[104:107], v[64:79]
	ds_read_b128 v[230:233], v250 offset:49152
	ds_read_b128 v[234:237], v250 offset:57344
	s_waitcnt lgkmcnt(4)
	v_mfma_f32_32x32x16_bf16 v[80:95], v[146:149], v[108:111], v[80:95]
	v_mfma_f32_32x32x16_bf16 v[64:79], v[150:153], v[108:111], v[64:79]
	ds_read_b128 v[146:149], v251 offset:49152
	ds_read_b128 v[150:153], v251 offset:57344
	v_exp_f32_e32 v212, v154
	s_waitcnt lgkmcnt(4)
	v_mfma_f32_32x32x16_bf16 v[80:95], v[222:225], v[112:115], v[80:95]
	v_mfma_f32_32x32x16_bf16 v[64:79], v[226:229], v[112:115], v[64:79]
	ds_read_b128 v[222:225], v252 offset:49152
	ds_read_b128 v[226:229], v252 offset:57344
	v_exp_f32_e32 v213, v155
	s_waitcnt lgkmcnt(4)
	v_mfma_f32_32x32x16_bf16 v[80:95], v[230:233], v[116:119], v[80:95]
	v_mfma_f32_32x32x16_bf16 v[64:79], v[234:237], v[116:119], v[64:79]
	v_exp_f32_e32 v214, v156
	s_waitcnt lgkmcnt(2)
	v_mfma_f32_32x32x16_bf16 v[80:95], v[146:149], v[120:123], v[80:95]
	v_mfma_f32_32x32x16_bf16 v[64:79], v[150:153], v[120:123], v[64:79]
	s_waitcnt lgkmcnt(0)
	v_mfma_f32_32x32x16_bf16 v[80:95], v[222:225], v[124:127], v[80:95]
	v_add_f32_e32 v146, 0, v167
	v_add_f32_e32 v146, v168, v146
	v_add_f32_e32 v146, v169, v146
	v_add_f32_e32 v146, v178, v146
	v_add_f32_e32 v146, v179, v146
	v_add_f32_e32 v146, v198, v146
	v_add_f32_e32 v146, v199, v146
	v_add_f32_e32 v146, v200, v146
	v_add_f32_e32 v146, v201, v146
	v_add_f32_e32 v146, v202, v146
	v_add_f32_e32 v146, v203, v146
	v_add_f32_e32 v146, v204, v146
	v_add_f32_e32 v146, v205, v146
	v_add_f32_e32 v146, v206, v146
	v_add_f32_e32 v146, v207, v146
	v_add_f32_e32 v146, v208, v146
	v_add_f32_e32 v146, v212, v146
	v_add_f32_e32 v146, v213, v146
	v_add_f32_e32 v146, v214, v146
	v_add_f32_e32 v146, v157, v146
	v_add_f32_e32 v146, v158, v146
	v_add_f32_e32 v146, v159, v146
	v_add_f32_e32 v146, v160, v146
	v_add_f32_e32 v146, v161, v146
	v_add_f32_e32 v146, v162, v146
	v_add_f32_e32 v146, v163, v146
	v_mfma_f32_32x32x16_bf16 v[64:79], v[226:229], v[124:127], v[64:79]
	v_add_f32_e32 v146, v164, v146
	v_add_f32_e32 v146, v165, v146
	v_add_f32_e32 v146, v166, v146
	v_add_f32_e32 v146, v209, v146
	v_add_f32_e32 v146, v210, v146
	v_add_f32_e32 v146, v211, v146
	v_mov_b32_e32 v147, v146
	s_nop 1
	v_permlane32_swap_b32_e32 v146, v147
	v_cvt_pk_bf16_f32 v148, v167, v168
	v_cvt_pk_bf16_f32 v149, v169, v178
	v_cvt_pk_bf16_f32 v150, v179, v198
	v_cvt_pk_bf16_f32 v151, v199, v200
	v_cvt_pk_bf16_f32 v152, v201, v202
	v_cvt_pk_bf16_f32 v153, v203, v204
	v_cvt_pk_bf16_f32 v154, v205, v206
	v_cvt_pk_bf16_f32 v155, v207, v208
	v_cvt_pk_bf16_f32 v156, v212, v213
	v_cvt_pk_bf16_f32 v157, v214, v157
	v_cvt_pk_bf16_f32 v158, v158, v159
	v_cvt_pk_bf16_f32 v159, v160, v161
	v_cvt_pk_bf16_f32 v160, v162, v163
	v_cvt_pk_bf16_f32 v161, v164, v165
	v_cvt_pk_bf16_f32 v162, v166, v209
	v_cvt_pk_bf16_f32 v163, v210, v211
	s_nop 0
	v_permlane32_swap_b32_e32 v148, v150
	v_permlane32_swap_b32_e32 v149, v151
	v_permlane32_swap_b32_e32 v152, v154
	v_permlane32_swap_b32_e32 v153, v155
	v_permlane32_swap_b32_e32 v156, v158
	v_permlane32_swap_b32_e32 v157, v159
	v_permlane32_swap_b32_e32 v160, v162
	v_permlane32_swap_b32_e32 v161, v163
	v_add_u32_e32 v168, s73, v192
	ds_read_b64_tr_b16 v[164:165], v168 offset:0
	ds_read_b64_tr_b16 v[166:167], v168 offset:0x800
	ds_read_b64_tr_b16 v[198:199], v168 offset:0x1000
	ds_read_b64_tr_b16 v[200:201], v168 offset:0x1800
	ds_read_b64_tr_b16 v[202:203], v168 offset:0x2000
	ds_read_b64_tr_b16 v[204:205], v168 offset:0x2800
	ds_read_b64_tr_b16 v[206:207], v168 offset:0x3000
	ds_read_b64_tr_b16 v[208:209], v168 offset:0x3800
	s_waitcnt lgkmcnt(4)
; #define SBAR() __builtin_amdgcn_sched_barrier(0)
; #define PV_RD(d0, kh, X) do { constexpr int b_ = v_rd_off(d0, 2 * (kh), 0); TRRD(X##l0, b_); TRRD(X##h0, b_ + 2048); TRRD(X##l1, b_ + 4096); TRRD(X##h1, b_ + 6144); } while (0)
; #define PV_MM(d0, X, PA, PB) do { \
;         o[d0] = __builtin_amdgcn_mfma_f32_32x32x16_bf16(PA, (bf16x8){X##l0[0], X##l0[1], X##l0[2], X##l0[3], X##h0[0], X##h0[1], X##h0[2], X##h0[3]}, o[d0], 0, 0, 0);   \
;         o[d0] = __builtin_amdgcn_mfma_f32_32x32x16_bf16(PB, (bf16x8){X##l1[0], X##l1[1], X##l1[2], X##l1[3], X##h1[0], X##h1[1], X##h1[2], X##h1[3]}, o[d0], 0, 0, 0); } while (0)
; #define PV_W4() do { asm volatile("s_waitcnt lgkmcnt(4)" ::: "memory"); SBAR(); } while (0)
; #define PV_W0() do { asm volatile("s_waitcnt lgkmcnt(0)" ::: "memory"); SBAR(); } while (0)
; __device__ __forceinline__ void mask_tile(f32x16& p0, f32x16& p1, int dq) {
;     const float NEG = -__builtin_inff();
; #pragma unroll
;     for (int r = 0; r < 16; ++r) { const int c = (r & 3) + 8 * (r >> 2); if (dq - c < 0) p0[r] = NEG; if (dq - c - 32 < 0) p1[r] = NEG; }
; }
; __device__ __forceinline__ void pv_tile(f32x16* o, int vb0, bf16x8 pa0, bf16x8 pa1, bf16x8 pa2, bf16x8 pa3) {
;     ...
;     s16x4 al0, al1, ah0, ah1, bl0, bl1, bh0, bh1;
;     PV_RD(0, 0, a);
;     PV_RD(0, 1, b); PV_W4(); PV_MM(0, a, pa0, pa1); SBAR();
;     PV_RD(1, 0, a); PV_W4(); PV_MM(0, b, pa2, pa3); SBAR();
;     PV_RD(1, 1, b); PV_W4(); PV_MM(1, a, pa0, pa1); SBAR();
;     PV_RD(2, 0, a); PV_W4(); PV_MM(1, b, pa2, pa3); SBAR();
;     PV_RD(2, 1, b); PV_W4(); PV_MM(2, a, pa0, pa1); SBAR();
;     PV_RD(3, 0, a); PV_W4(); PV_MM(2, b, pa2, pa3); SBAR();
;     PV_RD(3, 1, b); PV_W4(); PV_MM(3, a, pa0, pa1); SBAR();
;     PV_W0(); PV_MM(3, b, pa2, pa3);
	s_nop 0
	v_mfma_f32_32x32x16_bf16 v[48:63], v[148:151], v[164:167], v[48:63]
	v_mfma_f32_32x32x16_bf16 v[48:63], v[152:155], v[198:201], v[48:63]
	ds_read_b64_tr_b16 v[164:165], v168 offset:0x200
	ds_read_b64_tr_b16 v[166:167], v168 offset:0xa00
	ds_read_b64_tr_b16 v[198:199], v168 offset:0x1200
	ds_read_b64_tr_b16 v[200:201], v168 offset:0x1a00
	s_waitcnt lgkmcnt(4)
	v_mfma_f32_32x32x16_bf16 v[48:63], v[156:159], v[202:205], v[48:63]
	v_mfma_f32_32x32x16_bf16 v[48:63], v[160:163], v[206:209], v[48:63]
	ds_read_b64_tr_b16 v[202:203], v168 offset:0x2200
	ds_read_b64_tr_b16 v[204:205], v168 offset:0x2a00
	ds_read_b64_tr_b16 v[206:207], v168 offset:0x3200
	ds_read_b64_tr_b16 v[208:209], v168 offset:0x3a00
	s_waitcnt lgkmcnt(4)
	v_mfma_f32_32x32x16_bf16 v[32:47], v[148:151], v[164:167], v[32:47]
	v_mfma_f32_32x32x16_bf16 v[32:47], v[152:155], v[198:201], v[32:47]
	ds_read_b64_tr_b16 v[164:165], v168 offset:0x400
	ds_read_b64_tr_b16 v[166:167], v168 offset:0xc00
	ds_read_b64_tr_b16 v[198:199], v168 offset:0x1400
	ds_read_b64_tr_b16 v[200:201], v168 offset:0x1c00
	s_waitcnt lgkmcnt(4)
	v_mfma_f32_32x32x16_bf16 v[32:47], v[156:159], v[202:205], v[32:47]
	v_mfma_f32_32x32x16_bf16 v[32:47], v[160:163], v[206:209], v[32:47]
	ds_read_b64_tr_b16 v[202:203], v168 offset:0x2400
	ds_read_b64_tr_b16 v[204:205], v168 offset:0x2c00
	ds_read_b64_tr_b16 v[206:207], v168 offset:0x3400
	ds_read_b64_tr_b16 v[208:209], v168 offset:0x3c00
	s_waitcnt lgkmcnt(4)
	v_mfma_f32_32x32x16_bf16 v[16:31], v[148:151], v[164:167], v[16:31]
	v_mfma_f32_32x32x16_bf16 v[16:31], v[152:155], v[198:201], v[16:31]
	ds_read_b64_tr_b16 v[164:165], v168 offset:0x600
	ds_read_b64_tr_b16 v[166:167], v168 offset:0xe00
	ds_read_b64_tr_b16 v[198:199], v168 offset:0x1600
	ds_read_b64_tr_b16 v[200:201], v168 offset:0x1e00
	s_waitcnt lgkmcnt(4)
	v_mfma_f32_32x32x16_bf16 v[16:31], v[156:159], v[202:205], v[16:31]
	v_mfma_f32_32x32x16_bf16 v[16:31], v[160:163], v[206:209], v[16:31]
	ds_read_b64_tr_b16 v[202:203], v168 offset:0x2600
	ds_read_b64_tr_b16 v[204:205], v168 offset:0x2e00
	ds_read_b64_tr_b16 v[206:207], v168 offset:0x3600
	ds_read_b64_tr_b16 v[208:209], v168 offset:0x3e00
	s_waitcnt lgkmcnt(4)
	v_mfma_f32_32x32x16_bf16 v[0:15], v[148:151], v[164:167], v[0:15]
	v_mfma_f32_32x32x16_bf16 v[0:15], v[152:155], v[198:201], v[0:15]
	s_waitcnt lgkmcnt(0)
	v_mfma_f32_32x32x16_bf16 v[0:15], v[156:159], v[202:205], v[0:15]
	s_cmp_le_i32 s91, s88
	v_mfma_f32_32x32x16_bf16 v[0:15], v[160:163], v[206:209], v[0:15]
	s_cbranch_scc1 .LBB0_574
	v_subrev_u32_e32 v148, 64, v173
	v_cmp_gt_i32_e64 s[62:63], 26, v148
	v_cmp_gt_i32_e64 s[64:65], 27, v148
	v_cmp_gt_i32_e64 s[60:61], 25, v148
	s_and_b64 s[62:63], s[64:65], s[62:63]
	v_cmp_gt_i32_e64 s[58:59], 24, v148
	s_and_b64 s[60:61], s[62:63], s[60:61]
	v_cmp_gt_i32_e64 s[56:57], 19, v148
	s_and_b64 s[58:59], s[60:61], s[58:59]
	v_cmp_gt_i32_e64 s[54:55], 18, v148
	s_and_b64 s[56:57], s[58:59], s[56:57]
	v_cmp_gt_i32_e64 s[52:53], 17, v148
	s_and_b64 s[54:55], s[56:57], s[54:55]
	v_cmp_gt_i32_e64 s[50:51], 16, v148
	s_and_b64 s[52:53], s[54:55], s[52:53]
	v_cmp_gt_i32_e64 s[48:49], 11, v148
	s_and_b64 s[50:51], s[52:53], s[50:51]
	v_cmp_gt_i32_e64 s[46:47], 10, v148
	s_and_b64 s[48:49], s[50:51], s[48:49]
	v_cmp_gt_i32_e64 s[44:45], 9, v148
	s_and_b64 s[46:47], s[48:49], s[46:47]
	v_cmp_gt_i32_e64 s[42:43], 8, v148
	s_and_b64 s[44:45], s[46:47], s[44:45]
	v_cmp_gt_i32_e64 s[40:41], 3, v148
	s_and_b64 s[42:43], s[44:45], s[42:43]
	v_cmp_gt_i32_e64 s[38:39], 2, v148
	s_and_b64 s[40:41], s[42:43], s[40:41]
	v_cmp_gt_i32_e64 s[36:37], 1, v148
	s_and_b64 s[38:39], s[40:41], s[38:39]
	v_cmp_gt_i32_e64 s[34:35], 0, v148
	s_and_b64 s[36:37], s[38:39], s[36:37]
	s_and_b64 s[34:35], s[36:37], s[34:35]
	v_cmp_gt_i32_e64 s[28:29], 58, v148
	v_cndmask_b32_e64 v80, v80, v130, s[34:35]
	v_cmp_gt_i32_e64 s[34:35], 59, v148
	v_cmp_gt_i32_e64 s[26:27], 57, v148
	s_and_b64 s[28:29], s[34:35], s[28:29]
	v_cmp_gt_i32_e64 s[24:25], 56, v148
	s_and_b64 s[26:27], s[28:29], s[26:27]
	v_cmp_gt_i32_e64 s[22:23], 51, v148
	s_and_b64 s[24:25], s[26:27], s[24:25]
	v_cmp_gt_i32_e64 s[20:21], 50, v148
	s_and_b64 s[22:23], s[24:25], s[22:23]
	v_cmp_gt_i32_e64 s[18:19], 49, v148
	s_and_b64 s[20:21], s[22:23], s[20:21]
	v_cmp_gt_i32_e64 s[16:17], 48, v148
	s_and_b64 s[18:19], s[20:21], s[18:19]
	v_cmp_gt_i32_e64 s[14:15], 43, v148
	s_and_b64 s[16:17], s[18:19], s[16:17]
	v_cmp_gt_i32_e64 s[12:13], 42, v148
	s_and_b64 s[14:15], s[16:17], s[14:15]
	v_cmp_gt_i32_e64 s[10:11], 41, v148
	s_and_b64 s[12:13], s[14:15], s[12:13]
	v_cmp_gt_i32_e64 s[8:9], 40, v148
	s_and_b64 s[10:11], s[12:13], s[10:11]
	v_cmp_gt_i32_e64 s[6:7], 35, v148
	s_and_b64 s[8:9], s[10:11], s[8:9]
	v_cmp_gt_i32_e64 s[4:5], 34, v148
	s_and_b64 s[6:7], s[8:9], s[6:7]
	v_cmp_gt_i32_e64 s[2:3], 33, v148
	s_and_b64 s[4:5], s[6:7], s[4:5]
	v_cmp_gt_i32_e32 vcc, 32, v148
	s_and_b64 s[2:3], s[4:5], s[2:3]
	s_and_b64 vcc, s[2:3], vcc
	v_cndmask_b32_e64 v95, v95, v130, s[64:65]
	v_cndmask_b32_e64 v94, v94, v130, s[62:63]
	v_cndmask_b32_e64 v93, v93, v130, s[60:61]
	v_cndmask_b32_e64 v92, v92, v130, s[58:59]
	v_cndmask_b32_e64 v91, v91, v130, s[56:57]
	v_cndmask_b32_e64 v90, v90, v130, s[54:55]
	v_cndmask_b32_e64 v89, v89, v130, s[52:53]
	v_cndmask_b32_e64 v88, v88, v130, s[50:51]
	v_cndmask_b32_e64 v87, v87, v130, s[48:49]
	v_cndmask_b32_e64 v86, v86, v130, s[46:47]
	v_cndmask_b32_e64 v85, v85, v130, s[44:45]
	v_cndmask_b32_e64 v84, v84, v130, s[42:43]
	v_cndmask_b32_e64 v83, v83, v130, s[40:41]
	v_cndmask_b32_e64 v82, v82, v130, s[38:39]
	v_cndmask_b32_e64 v81, v81, v130, s[36:37]
	v_cndmask_b32_e64 v79, v79, v130, s[34:35]
	v_cndmask_b32_e64 v78, v78, v130, s[28:29]
	v_cndmask_b32_e64 v77, v77, v130, s[26:27]
	v_cndmask_b32_e64 v76, v76, v130, s[24:25]
	v_cndmask_b32_e64 v75, v75, v130, s[22:23]
	v_cndmask_b32_e64 v74, v74, v130, s[20:21]
	v_cndmask_b32_e64 v73, v73, v130, s[18:19]
	v_cndmask_b32_e64 v72, v72, v130, s[16:17]
	v_cndmask_b32_e64 v71, v71, v130, s[14:15]
	v_cndmask_b32_e64 v70, v70, v130, s[12:13]
	v_cndmask_b32_e64 v69, v69, v130, s[10:11]
	v_cndmask_b32_e64 v68, v68, v130, s[8:9]
	v_cndmask_b32_e64 v67, v67, v130, s[6:7]
	v_cndmask_b32_e64 v66, v66, v130, s[4:5]
	v_cndmask_b32_e64 v65, v65, v130, s[2:3]
	v_cndmask_b32_e32 v64, v64, v130, vcc

; __global__ void __launch_bounds__(NTHREADS, 2) fox_fwd(Args args) {
	.amdhsa_kernel _Z7fox_fwd4Args
		.amdhsa_group_segment_fixed_size 0
		.amdhsa_private_segment_fixed_size 0
		.amdhsa_kernarg_size 360
		.amdhsa_user_sgpr_count 2
		.amdhsa_user_sgpr_dispatch_ptr 0
		.amdhsa_user_sgpr_queue_ptr 0
		.amdhsa_user_sgpr_kernarg_segment_ptr 1
		.amdhsa_user_sgpr_dispatch_id 0
		.amdhsa_user_sgpr_kernarg_preload_length 0
		.amdhsa_user_sgpr_kernarg_preload_offset 0
		.amdhsa_user_sgpr_private_segment_size 0
		.amdhsa_uses_dynamic_stack 0
		.amdhsa_enable_private_segment 0
		.amdhsa_system_sgpr_workgroup_id_x 1
		.amdhsa_system_sgpr_workgroup_id_y 0
		.amdhsa_system_sgpr_workgroup_id_z 0
		.amdhsa_system_sgpr_workgroup_info 0
		.amdhsa_system_vgpr_workitem_id 2
		.amdhsa_next_free_vgpr 255
		.amdhsa_next_free_sgpr 102
		.amdhsa_accum_offset 256
		.amdhsa_reserve_vcc 1
		.amdhsa_float_round_mode_32 0
		.amdhsa_float_round_mode_16_64 0
		.amdhsa_float_denorm_mode_32 3
		.amdhsa_float_denorm_mode_16_64 3
		.amdhsa_dx10_clamp 1
		.amdhsa_ieee_mode 1
		.amdhsa_fp16_overflow 0
		.amdhsa_tg_split 0
		.amdhsa_exception_fp_ieee_invalid_op 0
		.amdhsa_exception_fp_denorm_src 0
		.amdhsa_exception_fp_ieee_div_zero 0
		.amdhsa_exception_fp_ieee_overflow 0
		.amdhsa_exception_fp_ieee_underflow 0
		.amdhsa_exception_fp_ieee_inexact 0
		.amdhsa_exception_int_div_zero 0
	.end_amdhsa_kernel

; __global__ void __launch_bounds__(NTHREADS, 2) fox_fwd(Args args) {
;     extern __shared__ __attribute__((aligned(16))) unsigned char lds[];
amdhsa.kernels:
  - .agpr_count:     0
    .args:
      - .offset:         0
        .size:           104
        .value_kind:     by_value
      - .offset:         104
        .size:           4
        .value_kind:     hidden_block_count_x
      - .offset:         108
        .size:           4
        .value_kind:     hidden_block_count_y
      - .offset:         112
        .size:           4
        .value_kind:     hidden_block_count_z
      - .offset:         116
        .size:           2
        .value_kind:     hidden_group_size_x
      - .offset:         118
        .size:           2
        .value_kind:     hidden_group_size_y
      - .offset:         120
        .size:           2
        .value_kind:     hidden_group_size_z
      - .offset:         122
        .size:           2
        .value_kind:     hidden_remainder_x
      - .offset:         124
        .size:           2
        .value_kind:     hidden_remainder_y
      - .offset:         126
        .size:           2
        .value_kind:     hidden_remainder_z
      - .offset:         144
        .size:           8
        .value_kind:     hidden_global_offset_x
      - .offset:         152
        .size:           8
        .value_kind:     hidden_global_offset_y
      - .offset:         160
        .size:           8
        .value_kind:     hidden_global_offset_z
      - .offset:         168
        .size:           2
        .value_kind:     hidden_grid_dims
      - .offset:         192
        .size:           8
        .value_kind:     hidden_multigrid_sync_arg
      - .offset:         224
        .size:           4
        .value_kind:     hidden_dynamic_lds_size
    .group_segment_fixed_size: 0
    .kernarg_segment_align: 8
    .kernarg_segment_size: 360
    .language:       OpenCL C
    .language_version:
      - 2
      - 0
    .max_flat_workgroup_size: 512
    .name:           _Z7fox_fwd4Args
    .private_segment_fixed_size: 0
    .sgpr_count:     104
    .sgpr_spill_count: 95
    .symbol:         _Z7fox_fwd4Args.kd
    .uniform_work_group_size: 1
    .uses_dynamic_stack: false
    .vgpr_count:     255
    .vgpr_spill_count: 0
    .wavefront_size: 64
